# P0: second-layer weight transposes deferred to the workgroups that idle in X1 of layers 0 and 1
# speedup vs baseline: 1.0203x; 1.0065x over previous
; #define LAS __attribute__((address_space(3)))
; #define SEG(cnt, ...) if (r < (cnt)) { p0_transpose_item(__VA_ARGS__); continue; } r -= (cnt);
; __device__ __forceinline__ void p0_transpose_item(const float* W, int K, int N, bf16_t* WT, int row_off, LAS float* scr, int item, int lane,
;                                                   const float* gain, int sc_lo, int sc_hi, float sc) {
;     const int nblk = N / 32, kb = item / nblk, nb = item % nblk, k0 = 64 * kb, n0 = 32 * nb;
;     f32x4 wv[8];
; #pragma unroll
;     for (int i = 0; i < 8; ++i) wv[i] = *(const f32x4*)(W + (size_t)(k0 + (lane >> 3) + 8 * i) * N + n0 + 4 * (lane & 7));
; #pragma unroll
;     for (int i = 0; i < 8; ++i) {
;         const int kk = (lane >> 3) + 8 * i;
;         const float gm = gain ? gain[k0 + kk] : 1.0f;
;         LAS float* sp = scr + kk * 33 + 4 * (lane & 7);
;         sp[0] = wv[i][0] * gm; sp[1] = wv[i][1] * gm; sp[2] = wv[i][2] * gm; sp[3] = wv[i][3] * gm;
;     }
;     asm volatile("s_waitcnt lgkmcnt(0)" ::: "memory");
; __global__ void __launch_bounds__(NTHREADS, 2) hybrid_fwd(Params P) {
;     ...
;             SEG(12288, w_in_ret + (size_t)2048 * RIN, 2048, RIN, WinR + (size_t)RIN * 2048, 0, scr, r, lane, norm_mix + 3 * 2048, 2048, 4096, 0.0625f)
.Lp0x_start:
	s_cmpk_lg_i32 s88, 0x100
	s_cbranch_scc1 .LBB0_1317
	s_cmpk_lt_i32 s90, 132
	s_cbranch_scc1 .LBB0_1317
	v_readlane_b32 s4, v254, 38
	v_readfirstlane_b32 s5, v139
	s_lshr_b32 s5, s5, 6
	s_cmp_gt_u32 s4, 1
	s_cbranch_scc1 .LBB0_1317
	s_sub_i32 s43, s90, 132
	s_lshl_b32 s43, s43, 3
	s_add_i32 s43, s43, s5
	s_movk_i32 s7, 0x3e0
	v_lshrrev_b32_e32 v2, 3, v215
	v_and_b32_e32 v3, 7, v215
	v_lshlrev_b32_e32 v5, 2, v2
	s_lshl_b32 s8, s5, 14
	v_mul_u32_u24_e32 v6, 0x84, v2
	v_lshl_add_u32 v6, v3, 4, v6
	v_add_u32_e32 v6, s8, v6
	v_mul_u32_u24_e32 v7, 0x420, v3
	v_lshl_add_u32 v7, v2, 2, v7
	v_add_u32_e32 v7, s8, v7
	s_cmp_eq_u32 s4, 1
	s_cbranch_scc1 .Lp0x_l1
	s_load_dwordx2 s[26:27], s[96:97], 0x80
	s_load_dwordx2 s[28:29], s[96:97], 0x40
	v_readlane_b32 s30, v254, 42
	v_readlane_b32 s31, v254, 43
	v_mul_u32_u24_e32 v4, 0xc000, v2
	v_lshl_add_u32 v4, v3, 4, v4
	v_mul_u32_u24_e32 v8, 0x1000, v2
	v_lshl_add_u32 v8, v3, 4, v8
	s_mov_b32 s6, s43
	s_waitcnt lgkmcnt(0)
	s_add_u32 s26, s26, 0x6000000
	s_addc_u32 s27, s27, 0
	s_add_u32 s28, s28, 0x6000
	s_addc_u32 s29, s29, 0
	s_add_u32 s30, s30, 0x6a00000
	s_addc_u32 s31, s31, 0
	s_cmpk_ge_i32 s6, 0x3000
	s_cbranch_scc1 .Lp0x_done_ir
	s_lshr_b32 s9, s6, 7
	s_mul_i32 s9, s9, 0xaaab
	s_lshr_b32 s9, s9, 17
	s_mul_i32 s12, s9, 0x180
	s_sub_i32 s12, s6, s12
	s_mul_i32 s13, s9, 0x300000
	s_lshl_b32 s34, s12, 7
	s_add_i32 s13, s13, s34
	s_add_u32 s36, s26, s13
	s_addc_u32 s37, s27, 0
	global_load_dwordx4 v[10:13], v4, s[36:37]
	s_add_u32 s36, s36, 0x60000
	s_addc_u32 s37, s37, 0
	global_load_dwordx4 v[14:17], v4, s[36:37]
	s_add_u32 s36, s36, 0x60000
	s_addc_u32 s37, s37, 0
	global_load_dwordx4 v[18:21], v4, s[36:37]
	s_add_u32 s36, s36, 0x60000
	s_addc_u32 s37, s37, 0
	global_load_dwordx4 v[22:25], v4, s[36:37]
	s_add_u32 s36, s36, 0x60000
	s_addc_u32 s37, s37, 0
	global_load_dwordx4 v[26:29], v4, s[36:37]
	s_add_u32 s36, s36, 0x60000
	s_addc_u32 s37, s37, 0
	global_load_dwordx4 v[30:33], v4, s[36:37]
	s_add_u32 s36, s36, 0x60000
	s_addc_u32 s37, s37, 0
	global_load_dwordx4 v[34:37], v4, s[36:37]
	s_add_u32 s36, s36, 0x60000
	s_addc_u32 s37, s37, 0
	global_load_dwordx4 v[38:41], v4, s[36:37]
	s_lshl_b32 s34, s9, 8
	s_add_u32 s38, s28, s34
	s_addc_u32 s39, s29, 0
	global_load_dword v42, v5, s[38:39]
	global_load_dword v43, v5, s[38:39] offset:32
	global_load_dword v44, v5, s[38:39] offset:64
	global_load_dword v45, v5, s[38:39] offset:96
	global_load_dword v46, v5, s[38:39] offset:128
	global_load_dword v47, v5, s[38:39] offset:160
	global_load_dword v48, v5, s[38:39] offset:192
	global_load_dword v49, v5, s[38:39] offset:224
.Lp0x_loop_ir:
	s_add_i32 s42, s6, s7
	s_cmpk_ge_i32 s42, 0x3000
	s_cbranch_scc1 .Lp0x_last_ir_A
	s_lshr_b32 s9, s42, 7
	s_mul_i32 s9, s9, 0xaaab
	s_lshr_b32 s9, s9, 17
	s_mul_i32 s12, s9, 0x180
	s_sub_i32 s12, s42, s12
	s_mul_i32 s13, s9, 0x300000
	s_lshl_b32 s34, s12, 7
	s_add_i32 s13, s13, s34
	s_add_u32 s36, s26, s13
	s_addc_u32 s37, s27, 0
	global_load_dwordx4 v[50:53], v4, s[36:37]
	s_add_u32 s36, s36, 0x60000
	s_addc_u32 s37, s37, 0
	global_load_dwordx4 v[54:57], v4, s[36:37]
	s_add_u32 s36, s36, 0x60000
	s_addc_u32 s37, s37, 0
	global_load_dwordx4 v[58:61], v4, s[36:37]
	s_add_u32 s36, s36, 0x60000
	s_addc_u32 s37, s37, 0
	global_load_dwordx4 v[62:65], v4, s[36:37]
	s_add_u32 s36, s36, 0x60000
	s_addc_u32 s37, s37, 0
	global_load_dwordx4 v[66:69], v4, s[36:37]
	s_add_u32 s36, s36, 0x60000
	s_addc_u32 s37, s37, 0
	global_load_dwordx4 v[70:73], v4, s[36:37]
	s_add_u32 s36, s36, 0x60000
	s_addc_u32 s37, s37, 0
	global_load_dwordx4 v[74:77], v4, s[36:37]
	s_add_u32 s36, s36, 0x60000
	s_addc_u32 s37, s37, 0
	global_load_dwordx4 v[78:81], v4, s[36:37]
	s_lshl_b32 s34, s9, 8
	s_add_u32 s38, s28, s34
	s_addc_u32 s39, s29, 0
	global_load_dword v82, v5, s[38:39]
	global_load_dword v83, v5, s[38:39] offset:32
	global_load_dword v84, v5, s[38:39] offset:64
	global_load_dword v85, v5, s[38:39] offset:96
	global_load_dword v86, v5, s[38:39] offset:128
	global_load_dword v87, v5, s[38:39] offset:160
	global_load_dword v88, v5, s[38:39] offset:192
	global_load_dword v89, v5, s[38:39] offset:224
	s_waitcnt vmcnt(16)
	s_lshr_b32 s9, s6, 7
	s_mul_i32 s9, s9, 0xaaab
	s_lshr_b32 s9, s9, 17
	s_mul_i32 s12, s9, 0x180
	s_sub_i32 s12, s6, s12
	v_mul_f32_e32 v10, v10, v42
	v_mul_f32_e32 v11, v11, v42
	v_mul_f32_e32 v12, v12, v42
	v_mul_f32_e32 v13, v13, v42
	ds_write2_b32 v6, v10, v11 offset1:1
	ds_write2_b32 v6, v12, v13 offset0:2 offset1:3
	v_mul_f32_e32 v14, v14, v43
	v_mul_f32_e32 v15, v15, v43
	v_mul_f32_e32 v16, v16, v43
	v_mul_f32_e32 v17, v17, v43
	v_add_u32_e32 v0, 0x420, v6
	ds_write2_b32 v0, v14, v15 offset1:1
	ds_write2_b32 v0, v16, v17 offset0:2 offset1:3
	v_mul_f32_e32 v18, v18, v44
	v_mul_f32_e32 v19, v19, v44
	v_mul_f32_e32 v20, v20, v44
	v_mul_f32_e32 v21, v21, v44
	v_add_u32_e32 v0, 0x840, v6
	ds_write2_b32 v0, v18, v19 offset1:1
	ds_write2_b32 v0, v20, v21 offset0:2 offset1:3
	v_mul_f32_e32 v22, v22, v45
	v_mul_f32_e32 v23, v23, v45
	v_mul_f32_e32 v24, v24, v45
	v_mul_f32_e32 v25, v25, v45
	v_add_u32_e32 v0, 0xc60, v6
	ds_write2_b32 v0, v22, v23 offset1:1
	ds_write2_b32 v0, v24, v25 offset0:2 offset1:3
	v_mul_f32_e32 v26, v26, v46
	v_mul_f32_e32 v27, v27, v46
	v_mul_f32_e32 v28, v28, v46
	v_mul_f32_e32 v29, v29, v46
	v_add_u32_e32 v0, 0x1080, v6
	ds_write2_b32 v0, v26, v27 offset1:1
	ds_write2_b32 v0, v28, v29 offset0:2 offset1:3
	v_mul_f32_e32 v30, v30, v47
	v_mul_f32_e32 v31, v31, v47
	v_mul_f32_e32 v32, v32, v47
	v_mul_f32_e32 v33, v33, v47
	v_add_u32_e32 v0, 0x14a0, v6
	ds_write2_b32 v0, v30, v31 offset1:1
	ds_write2_b32 v0, v32, v33 offset0:2 offset1:3
	v_mul_f32_e32 v34, v34, v48
	v_mul_f32_e32 v35, v35, v48
	v_mul_f32_e32 v36, v36, v48
	v_mul_f32_e32 v37, v37, v48
	v_add_u32_e32 v0, 0x18c0, v6
	ds_write2_b32 v0, v34, v35 offset1:1
	ds_write2_b32 v0, v36, v37 offset0:2 offset1:3
	v_mul_f32_e32 v38, v38, v49
	v_mul_f32_e32 v39, v39, v49
	v_mul_f32_e32 v40, v40, v49
	v_mul_f32_e32 v41, v41, v49
	v_add_u32_e32 v0, 0x1ce0, v6
	ds_write2_b32 v0, v38, v39 offset1:1
	ds_write2_b32 v0, v40, v41 offset0:2 offset1:3
	s_waitcnt lgkmcnt(0)
; #define LAS __attribute__((address_space(3)))
; __device__ __forceinline__ unsigned pk2(float lo, float hi) { return pg8::cvt_pk_bf16(lo, hi); }
; __device__ __forceinline__ void p0_transpose_item(const float* W, int K, int N, bf16_t* WT, int row_off, LAS float* scr, int item, int lane,
;                                                   const float* gain, int sc_lo, int sc_hi, float sc) {
;     ...
;     const int c = lane & 7;
; #pragma unroll
;     for (int j = 0; j < 4; ++j) {
;         const int n = (lane >> 3) + 8 * j; const LAS float* s = scr + (8 * c) * 33 + n;
;         const float mlt = (n0 + n >= sc_lo && n0 + n < sc_hi) ? sc : 1.0f;
;         u32x4 o; o.x = pk2(s[0 * 33] * mlt, s[1 * 33] * mlt); o.y = pk2(s[2 * 33] * mlt, s[3 * 33] * mlt);
;         o.z = pk2(s[4 * 33] * mlt, s[5 * 33] * mlt); o.w = pk2(s[6 * 33] * mlt, s[7 * 33] * mlt);
;         *(u32x4*)(WT + (size_t)(row_off + n0 + n) * K + k0 + 8 * c) = o;
;     }
	ds_read_b32 v90, v7 offset:0
	ds_read_b32 v91, v7 offset:132
	ds_read_b32 v92, v7 offset:264
	ds_read_b32 v93, v7 offset:396
	ds_read_b32 v94, v7 offset:528
	ds_read_b32 v95, v7 offset:660
	ds_read_b32 v96, v7 offset:792
	ds_read_b32 v97, v7 offset:924
	ds_read_b32 v98, v7 offset:32
	ds_read_b32 v99, v7 offset:164
	ds_read_b32 v100, v7 offset:296
	ds_read_b32 v101, v7 offset:428
	ds_read_b32 v102, v7 offset:560
	ds_read_b32 v103, v7 offset:692
	ds_read_b32 v104, v7 offset:824
	ds_read_b32 v105, v7 offset:956
	ds_read_b32 v106, v7 offset:64
	ds_read_b32 v107, v7 offset:196
	ds_read_b32 v108, v7 offset:328
	ds_read_b32 v109, v7 offset:460
	ds_read_b32 v110, v7 offset:592
	ds_read_b32 v111, v7 offset:724
	ds_read_b32 v112, v7 offset:856
	ds_read_b32 v113, v7 offset:988
	ds_read_b32 v114, v7 offset:96
	ds_read_b32 v115, v7 offset:228
	ds_read_b32 v116, v7 offset:360
	ds_read_b32 v117, v7 offset:492
	ds_read_b32 v118, v7 offset:624
	ds_read_b32 v119, v7 offset:756
	ds_read_b32 v120, v7 offset:888
	ds_read_b32 v121, v7 offset:1020
	s_sub_i32 s13, s12, 64
	s_cmp_lt_u32 s13, 64
	s_waitcnt lgkmcnt(0)
	s_cbranch_scc0 .Lp0x_nm_ir_A
	v_mul_f32_e32 v90, 0x3d800000, v90
	v_mul_f32_e32 v91, 0x3d800000, v91
	v_mul_f32_e32 v92, 0x3d800000, v92
	v_mul_f32_e32 v93, 0x3d800000, v93
	v_mul_f32_e32 v94, 0x3d800000, v94
	v_mul_f32_e32 v95, 0x3d800000, v95
	v_mul_f32_e32 v96, 0x3d800000, v96
	v_mul_f32_e32 v97, 0x3d800000, v97
	v_mul_f32_e32 v98, 0x3d800000, v98
	v_mul_f32_e32 v99, 0x3d800000, v99
	v_mul_f32_e32 v100, 0x3d800000, v100
	v_mul_f32_e32 v101, 0x3d800000, v101
	v_mul_f32_e32 v102, 0x3d800000, v102
	v_mul_f32_e32 v103, 0x3d800000, v103
	v_mul_f32_e32 v104, 0x3d800000, v104
	v_mul_f32_e32 v105, 0x3d800000, v105
	v_mul_f32_e32 v106, 0x3d800000, v106
	v_mul_f32_e32 v107, 0x3d800000, v107
	v_mul_f32_e32 v108, 0x3d800000, v108
	v_mul_f32_e32 v109, 0x3d800000, v109
	v_mul_f32_e32 v110, 0x3d800000, v110
	v_mul_f32_e32 v111, 0x3d800000, v111
	v_mul_f32_e32 v112, 0x3d800000, v112
	v_mul_f32_e32 v113, 0x3d800000, v113
	v_mul_f32_e32 v114, 0x3d800000, v114
	v_mul_f32_e32 v115, 0x3d800000, v115
	v_mul_f32_e32 v116, 0x3d800000, v116
	v_mul_f32_e32 v117, 0x3d800000, v117
	v_mul_f32_e32 v118, 0x3d800000, v118
	v_mul_f32_e32 v119, 0x3d800000, v119
	v_mul_f32_e32 v120, 0x3d800000, v120
	v_mul_f32_e32 v121, 0x3d800000, v121
.Lp0x_nm_ir_A:
	s_mul_i32 s34, s12, 0x20000
	s_lshl_b32 s35, s9, 7
	s_add_i32 s34, s34, s35
	s_add_u32 s40, s30, s34
	s_addc_u32 s41, s31, 0
	v_cvt_pk_bf16_f32 v122, v90, v91
	v_cvt_pk_bf16_f32 v123, v92, v93
	v_cvt_pk_bf16_f32 v124, v94, v95
	v_cvt_pk_bf16_f32 v125, v96, v97
	global_store_dwordx4 v8, v[122:125], s[40:41]
	s_add_u32 s40, s40, 0x8000
	s_addc_u32 s41, s41, 0
	v_cvt_pk_bf16_f32 v126, v98, v99
	v_cvt_pk_bf16_f32 v127, v100, v101
	v_cvt_pk_bf16_f32 v128, v102, v103
	v_cvt_pk_bf16_f32 v129, v104, v105
	global_store_dwordx4 v8, v[126:129], s[40:41]
	s_add_u32 s40, s40, 0x8000
	s_addc_u32 s41, s41, 0
	v_cvt_pk_bf16_f32 v130, v106, v107
	v_cvt_pk_bf16_f32 v131, v108, v109
	v_cvt_pk_bf16_f32 v132, v110, v111
	v_cvt_pk_bf16_f32 v133, v112, v113
	global_store_dwordx4 v8, v[130:133], s[40:41]
	s_add_u32 s40, s40, 0x8000
	s_addc_u32 s41, s41, 0
	v_cvt_pk_bf16_f32 v134, v114, v115
	v_cvt_pk_bf16_f32 v135, v116, v117
	v_cvt_pk_bf16_f32 v136, v118, v119
	v_cvt_pk_bf16_f32 v137, v120, v121
	global_store_dwordx4 v8, v[134:137], s[40:41]
	s_add_i32 s6, s42, s7
	s_cmpk_ge_i32 s6, 0x3000
	s_cbranch_scc1 .Lp0x_last_ir_B
	s_lshr_b32 s9, s6, 7
	s_mul_i32 s9, s9, 0xaaab
	s_lshr_b32 s9, s9, 17
	s_mul_i32 s12, s9, 0x180
	s_sub_i32 s12, s6, s12
	s_mul_i32 s13, s9, 0x300000
	s_lshl_b32 s34, s12, 7
	s_add_i32 s13, s13, s34
	s_add_u32 s36, s26, s13
	s_addc_u32 s37, s27, 0
	global_load_dwordx4 v[10:13], v4, s[36:37]
	s_add_u32 s36, s36, 0x60000
	s_addc_u32 s37, s37, 0
	global_load_dwordx4 v[14:17], v4, s[36:37]
	s_add_u32 s36, s36, 0x60000
	s_addc_u32 s37, s37, 0
	global_load_dwordx4 v[18:21], v4, s[36:37]
	s_add_u32 s36, s36, 0x60000
	s_addc_u32 s37, s37, 0
	global_load_dwordx4 v[22:25], v4, s[36:37]
	s_add_u32 s36, s36, 0x60000
	s_addc_u32 s37, s37, 0
	global_load_dwordx4 v[26:29], v4, s[36:37]
	s_add_u32 s36, s36, 0x60000
	s_addc_u32 s37, s37, 0
	global_load_dwordx4 v[30:33], v4, s[36:37]
	s_add_u32 s36, s36, 0x60000
	s_addc_u32 s37, s37, 0
	global_load_dwordx4 v[34:37], v4, s[36:37]
	s_add_u32 s36, s36, 0x60000
	s_addc_u32 s37, s37, 0
	global_load_dwordx4 v[38:41], v4, s[36:37]
	s_lshl_b32 s34, s9, 8
	s_add_u32 s38, s28, s34
	s_addc_u32 s39, s29, 0
	global_load_dword v42, v5, s[38:39]
	global_load_dword v43, v5, s[38:39] offset:32
	global_load_dword v44, v5, s[38:39] offset:64
	global_load_dword v45, v5, s[38:39] offset:96
	global_load_dword v46, v5, s[38:39] offset:128
	global_load_dword v47, v5, s[38:39] offset:160
	global_load_dword v48, v5, s[38:39] offset:192
	global_load_dword v49, v5, s[38:39] offset:224
	s_waitcnt vmcnt(16)
; #define LAS __attribute__((address_space(3)))
; __device__ __forceinline__ unsigned pk2(float lo, float hi) { return pg8::cvt_pk_bf16(lo, hi); }
; __device__ __forceinline__ void p0_transpose_item(const float* W, int K, int N, bf16_t* WT, int row_off, LAS float* scr, int item, int lane,
;                                                   const float* gain, int sc_lo, int sc_hi, float sc) {
;     ...
;     for (int i = 0; i < 8; ++i) {
;         const int kk = (lane >> 3) + 8 * i;
;         const float gm = gain ? gain[k0 + kk] : 1.0f;
;         LAS float* sp = scr + kk * 33 + 4 * (lane & 7);
;         sp[0] = wv[i][0] * gm; sp[1] = wv[i][1] * gm; sp[2] = wv[i][2] * gm; sp[3] = wv[i][3] * gm;
;     }
;     asm volatile("s_waitcnt lgkmcnt(0)" ::: "memory");
;     const int c = lane & 7;
; #pragma unroll
;     for (int j = 0; j < 4; ++j) {
;         const int n = (lane >> 3) + 8 * j; const LAS float* s = scr + (8 * c) * 33 + n;
;         const float mlt = (n0 + n >= sc_lo && n0 + n < sc_hi) ? sc : 1.0f;
;         u32x4 o; o.x = pk2(s[0 * 33] * mlt, s[1 * 33] * mlt); o.y = pk2(s[2 * 33] * mlt, s[3 * 33] * mlt);
;         o.z = pk2(s[4 * 33] * mlt, s[5 * 33] * mlt); o.w = pk2(s[6 * 33] * mlt, s[7 * 33] * mlt);
;         *(u32x4*)(WT + (size_t)(row_off + n0 + n) * K + k0 + 8 * c) = o;
;     }
	s_lshr_b32 s9, s42, 7
	s_mul_i32 s9, s9, 0xaaab
	s_lshr_b32 s9, s9, 17
	s_mul_i32 s12, s9, 0x180
	s_sub_i32 s12, s42, s12
	v_mul_f32_e32 v50, v50, v82
	v_mul_f32_e32 v51, v51, v82
	v_mul_f32_e32 v52, v52, v82
	v_mul_f32_e32 v53, v53, v82
	ds_write2_b32 v6, v50, v51 offset1:1
	ds_write2_b32 v6, v52, v53 offset0:2 offset1:3
	v_mul_f32_e32 v54, v54, v83
	v_mul_f32_e32 v55, v55, v83
	v_mul_f32_e32 v56, v56, v83
	v_mul_f32_e32 v57, v57, v83
	v_add_u32_e32 v0, 0x420, v6
	ds_write2_b32 v0, v54, v55 offset1:1
	ds_write2_b32 v0, v56, v57 offset0:2 offset1:3
	v_mul_f32_e32 v58, v58, v84
	v_mul_f32_e32 v59, v59, v84
	v_mul_f32_e32 v60, v60, v84
	v_mul_f32_e32 v61, v61, v84
	v_add_u32_e32 v0, 0x840, v6
	ds_write2_b32 v0, v58, v59 offset1:1
	ds_write2_b32 v0, v60, v61 offset0:2 offset1:3
	v_mul_f32_e32 v62, v62, v85
	v_mul_f32_e32 v63, v63, v85
	v_mul_f32_e32 v64, v64, v85
	v_mul_f32_e32 v65, v65, v85
	v_add_u32_e32 v0, 0xc60, v6
	ds_write2_b32 v0, v62, v63 offset1:1
	ds_write2_b32 v0, v64, v65 offset0:2 offset1:3
	v_mul_f32_e32 v66, v66, v86
	v_mul_f32_e32 v67, v67, v86
	v_mul_f32_e32 v68, v68, v86
	v_mul_f32_e32 v69, v69, v86
	v_add_u32_e32 v0, 0x1080, v6
	ds_write2_b32 v0, v66, v67 offset1:1
	ds_write2_b32 v0, v68, v69 offset0:2 offset1:3
	v_mul_f32_e32 v70, v70, v87
	v_mul_f32_e32 v71, v71, v87
	v_mul_f32_e32 v72, v72, v87
	v_mul_f32_e32 v73, v73, v87
	v_add_u32_e32 v0, 0x14a0, v6
	ds_write2_b32 v0, v70, v71 offset1:1
	ds_write2_b32 v0, v72, v73 offset0:2 offset1:3
	v_mul_f32_e32 v74, v74, v88
	v_mul_f32_e32 v75, v75, v88
	v_mul_f32_e32 v76, v76, v88
	v_mul_f32_e32 v77, v77, v88
	v_add_u32_e32 v0, 0x18c0, v6
	ds_write2_b32 v0, v74, v75 offset1:1
	ds_write2_b32 v0, v76, v77 offset0:2 offset1:3
	v_mul_f32_e32 v78, v78, v89
	v_mul_f32_e32 v79, v79, v89
	v_mul_f32_e32 v80, v80, v89
	v_mul_f32_e32 v81, v81, v89
	v_add_u32_e32 v0, 0x1ce0, v6
	ds_write2_b32 v0, v78, v79 offset1:1
	ds_write2_b32 v0, v80, v81 offset0:2 offset1:3
	s_waitcnt lgkmcnt(0)
	ds_read_b32 v90, v7 offset:0
	ds_read_b32 v91, v7 offset:132
	ds_read_b32 v92, v7 offset:264
	ds_read_b32 v93, v7 offset:396
	ds_read_b32 v94, v7 offset:528
	ds_read_b32 v95, v7 offset:660
	ds_read_b32 v96, v7 offset:792
	ds_read_b32 v97, v7 offset:924
	ds_read_b32 v98, v7 offset:32
	ds_read_b32 v99, v7 offset:164
	ds_read_b32 v100, v7 offset:296
	ds_read_b32 v101, v7 offset:428
	ds_read_b32 v102, v7 offset:560
	ds_read_b32 v103, v7 offset:692
	ds_read_b32 v104, v7 offset:824
	ds_read_b32 v105, v7 offset:956
	ds_read_b32 v106, v7 offset:64
	ds_read_b32 v107, v7 offset:196
	ds_read_b32 v108, v7 offset:328
	ds_read_b32 v109, v7 offset:460
	ds_read_b32 v110, v7 offset:592
	ds_read_b32 v111, v7 offset:724
	ds_read_b32 v112, v7 offset:856
	ds_read_b32 v113, v7 offset:988
	ds_read_b32 v114, v7 offset:96
	ds_read_b32 v115, v7 offset:228
	ds_read_b32 v116, v7 offset:360
	ds_read_b32 v117, v7 offset:492
	ds_read_b32 v118, v7 offset:624
	ds_read_b32 v119, v7 offset:756
	ds_read_b32 v120, v7 offset:888
	ds_read_b32 v121, v7 offset:1020
	s_sub_i32 s13, s12, 64
	s_cmp_lt_u32 s13, 64
	s_waitcnt lgkmcnt(0)
	s_cbranch_scc0 .Lp0x_nm_ir_B
	v_mul_f32_e32 v90, 0x3d800000, v90
	v_mul_f32_e32 v91, 0x3d800000, v91
	v_mul_f32_e32 v92, 0x3d800000, v92
	v_mul_f32_e32 v93, 0x3d800000, v93
	v_mul_f32_e32 v94, 0x3d800000, v94
	v_mul_f32_e32 v95, 0x3d800000, v95
	v_mul_f32_e32 v96, 0x3d800000, v96
	v_mul_f32_e32 v97, 0x3d800000, v97
	v_mul_f32_e32 v98, 0x3d800000, v98
	v_mul_f32_e32 v99, 0x3d800000, v99
	v_mul_f32_e32 v100, 0x3d800000, v100
	v_mul_f32_e32 v101, 0x3d800000, v101
	v_mul_f32_e32 v102, 0x3d800000, v102
	v_mul_f32_e32 v103, 0x3d800000, v103
	v_mul_f32_e32 v104, 0x3d800000, v104
	v_mul_f32_e32 v105, 0x3d800000, v105
	v_mul_f32_e32 v106, 0x3d800000, v106
	v_mul_f32_e32 v107, 0x3d800000, v107
	v_mul_f32_e32 v108, 0x3d800000, v108
	v_mul_f32_e32 v109, 0x3d800000, v109
	v_mul_f32_e32 v110, 0x3d800000, v110
	v_mul_f32_e32 v111, 0x3d800000, v111
	v_mul_f32_e32 v112, 0x3d800000, v112
	v_mul_f32_e32 v113, 0x3d800000, v113
	v_mul_f32_e32 v114, 0x3d800000, v114
	v_mul_f32_e32 v115, 0x3d800000, v115
	v_mul_f32_e32 v116, 0x3d800000, v116
	v_mul_f32_e32 v117, 0x3d800000, v117
	v_mul_f32_e32 v118, 0x3d800000, v118
	v_mul_f32_e32 v119, 0x3d800000, v119
	v_mul_f32_e32 v120, 0x3d800000, v120
	v_mul_f32_e32 v121, 0x3d800000, v121
.Lp0x_nm_ir_B:
	s_mul_i32 s34, s12, 0x20000
	s_lshl_b32 s35, s9, 7
	s_add_i32 s34, s34, s35
	s_add_u32 s40, s30, s34
	s_addc_u32 s41, s31, 0
	v_cvt_pk_bf16_f32 v122, v90, v91
	v_cvt_pk_bf16_f32 v123, v92, v93
	v_cvt_pk_bf16_f32 v124, v94, v95
	v_cvt_pk_bf16_f32 v125, v96, v97
	global_store_dwordx4 v8, v[122:125], s[40:41]
	s_add_u32 s40, s40, 0x8000
	s_addc_u32 s41, s41, 0
	v_cvt_pk_bf16_f32 v126, v98, v99
	v_cvt_pk_bf16_f32 v127, v100, v101
	v_cvt_pk_bf16_f32 v128, v102, v103
	v_cvt_pk_bf16_f32 v129, v104, v105
	global_store_dwordx4 v8, v[126:129], s[40:41]
	s_add_u32 s40, s40, 0x8000
	s_addc_u32 s41, s41, 0
	v_cvt_pk_bf16_f32 v130, v106, v107
	v_cvt_pk_bf16_f32 v131, v108, v109
	v_cvt_pk_bf16_f32 v132, v110, v111
	v_cvt_pk_bf16_f32 v133, v112, v113
	global_store_dwordx4 v8, v[130:133], s[40:41]
	s_add_u32 s40, s40, 0x8000
	s_addc_u32 s41, s41, 0
	v_cvt_pk_bf16_f32 v134, v114, v115
	v_cvt_pk_bf16_f32 v135, v116, v117
	v_cvt_pk_bf16_f32 v136, v118, v119
	v_cvt_pk_bf16_f32 v137, v120, v121
	global_store_dwordx4 v8, v[134:137], s[40:41]
	s_branch .Lp0x_loop_ir
; #define LAS __attribute__((address_space(3)))
; __device__ __forceinline__ unsigned pk2(float lo, float hi) { return pg8::cvt_pk_bf16(lo, hi); }
; __device__ __forceinline__ void p0_transpose_item(const float* W, int K, int N, bf16_t* WT, int row_off, LAS float* scr, int item, int lane,
;                                                   const float* gain, int sc_lo, int sc_hi, float sc) {
;     ...
;     for (int i = 0; i < 8; ++i) {
;         const int kk = (lane >> 3) + 8 * i;
;         const float gm = gain ? gain[k0 + kk] : 1.0f;
;         LAS float* sp = scr + kk * 33 + 4 * (lane & 7);
;         sp[0] = wv[i][0] * gm; sp[1] = wv[i][1] * gm; sp[2] = wv[i][2] * gm; sp[3] = wv[i][3] * gm;
;     }
;     asm volatile("s_waitcnt lgkmcnt(0)" ::: "memory");
;     const int c = lane & 7;
; #pragma unroll
;     for (int j = 0; j < 4; ++j) {
;         const int n = (lane >> 3) + 8 * j; const LAS float* s = scr + (8 * c) * 33 + n;
;         const float mlt = (n0 + n >= sc_lo && n0 + n < sc_hi) ? sc : 1.0f;
;         u32x4 o; o.x = pk2(s[0 * 33] * mlt, s[1 * 33] * mlt); o.y = pk2(s[2 * 33] * mlt, s[3 * 33] * mlt);
.Lp0x_last_ir_A:
	s_waitcnt vmcnt(0)
	s_lshr_b32 s9, s6, 7
	s_mul_i32 s9, s9, 0xaaab
	s_lshr_b32 s9, s9, 17
	s_mul_i32 s12, s9, 0x180
	s_sub_i32 s12, s6, s12
	v_mul_f32_e32 v10, v10, v42
	v_mul_f32_e32 v11, v11, v42
	v_mul_f32_e32 v12, v12, v42
	v_mul_f32_e32 v13, v13, v42
	ds_write2_b32 v6, v10, v11 offset1:1
	ds_write2_b32 v6, v12, v13 offset0:2 offset1:3
	v_mul_f32_e32 v14, v14, v43
	v_mul_f32_e32 v15, v15, v43
	v_mul_f32_e32 v16, v16, v43
	v_mul_f32_e32 v17, v17, v43
	v_add_u32_e32 v0, 0x420, v6
	ds_write2_b32 v0, v14, v15 offset1:1
	ds_write2_b32 v0, v16, v17 offset0:2 offset1:3
	v_mul_f32_e32 v18, v18, v44
	v_mul_f32_e32 v19, v19, v44
	v_mul_f32_e32 v20, v20, v44
	v_mul_f32_e32 v21, v21, v44
	v_add_u32_e32 v0, 0x840, v6
	ds_write2_b32 v0, v18, v19 offset1:1
	ds_write2_b32 v0, v20, v21 offset0:2 offset1:3
	v_mul_f32_e32 v22, v22, v45
	v_mul_f32_e32 v23, v23, v45
	v_mul_f32_e32 v24, v24, v45
	v_mul_f32_e32 v25, v25, v45
	v_add_u32_e32 v0, 0xc60, v6
	ds_write2_b32 v0, v22, v23 offset1:1
	ds_write2_b32 v0, v24, v25 offset0:2 offset1:3
	v_mul_f32_e32 v26, v26, v46
	v_mul_f32_e32 v27, v27, v46
	v_mul_f32_e32 v28, v28, v46
	v_mul_f32_e32 v29, v29, v46
	v_add_u32_e32 v0, 0x1080, v6
	ds_write2_b32 v0, v26, v27 offset1:1
	ds_write2_b32 v0, v28, v29 offset0:2 offset1:3
	v_mul_f32_e32 v30, v30, v47
	v_mul_f32_e32 v31, v31, v47
	v_mul_f32_e32 v32, v32, v47
	v_mul_f32_e32 v33, v33, v47
	v_add_u32_e32 v0, 0x14a0, v6
	ds_write2_b32 v0, v30, v31 offset1:1
	ds_write2_b32 v0, v32, v33 offset0:2 offset1:3
	v_mul_f32_e32 v34, v34, v48
	v_mul_f32_e32 v35, v35, v48
	v_mul_f32_e32 v36, v36, v48
	v_mul_f32_e32 v37, v37, v48
	v_add_u32_e32 v0, 0x18c0, v6
	ds_write2_b32 v0, v34, v35 offset1:1
	ds_write2_b32 v0, v36, v37 offset0:2 offset1:3
	v_mul_f32_e32 v38, v38, v49
	v_mul_f32_e32 v39, v39, v49
	v_mul_f32_e32 v40, v40, v49
	v_mul_f32_e32 v41, v41, v49
	v_add_u32_e32 v0, 0x1ce0, v6
	ds_write2_b32 v0, v38, v39 offset1:1
	ds_write2_b32 v0, v40, v41 offset0:2 offset1:3
	s_waitcnt lgkmcnt(0)
	ds_read_b32 v90, v7 offset:0
	ds_read_b32 v91, v7 offset:132
	ds_read_b32 v92, v7 offset:264
	ds_read_b32 v93, v7 offset:396
	ds_read_b32 v94, v7 offset:528
	ds_read_b32 v95, v7 offset:660
	ds_read_b32 v96, v7 offset:792
	ds_read_b32 v97, v7 offset:924
	ds_read_b32 v98, v7 offset:32
	ds_read_b32 v99, v7 offset:164
	ds_read_b32 v100, v7 offset:296
	ds_read_b32 v101, v7 offset:428
	ds_read_b32 v102, v7 offset:560
	ds_read_b32 v103, v7 offset:692
	ds_read_b32 v104, v7 offset:824
	ds_read_b32 v105, v7 offset:956
	ds_read_b32 v106, v7 offset:64
	ds_read_b32 v107, v7 offset:196
	ds_read_b32 v108, v7 offset:328
	ds_read_b32 v109, v7 offset:460
	ds_read_b32 v110, v7 offset:592
	ds_read_b32 v111, v7 offset:724
	ds_read_b32 v112, v7 offset:856
	ds_read_b32 v113, v7 offset:988
	ds_read_b32 v114, v7 offset:96
	ds_read_b32 v115, v7 offset:228
	ds_read_b32 v116, v7 offset:360
	ds_read_b32 v117, v7 offset:492
	ds_read_b32 v118, v7 offset:624
	ds_read_b32 v119, v7 offset:756
	ds_read_b32 v120, v7 offset:888
	ds_read_b32 v121, v7 offset:1020
	s_sub_i32 s13, s12, 64
	s_cmp_lt_u32 s13, 64
	s_waitcnt lgkmcnt(0)
	s_cbranch_scc0 .Lp0x_nm_ir_tA
	v_mul_f32_e32 v90, 0x3d800000, v90
	v_mul_f32_e32 v91, 0x3d800000, v91
	v_mul_f32_e32 v92, 0x3d800000, v92
	v_mul_f32_e32 v93, 0x3d800000, v93
	v_mul_f32_e32 v94, 0x3d800000, v94
	v_mul_f32_e32 v95, 0x3d800000, v95
	v_mul_f32_e32 v96, 0x3d800000, v96
	v_mul_f32_e32 v97, 0x3d800000, v97
	v_mul_f32_e32 v98, 0x3d800000, v98
	v_mul_f32_e32 v99, 0x3d800000, v99
	v_mul_f32_e32 v100, 0x3d800000, v100
	v_mul_f32_e32 v101, 0x3d800000, v101
	v_mul_f32_e32 v102, 0x3d800000, v102
	v_mul_f32_e32 v103, 0x3d800000, v103
	v_mul_f32_e32 v104, 0x3d800000, v104
	v_mul_f32_e32 v105, 0x3d800000, v105
	v_mul_f32_e32 v106, 0x3d800000, v106
	v_mul_f32_e32 v107, 0x3d800000, v107
	v_mul_f32_e32 v108, 0x3d800000, v108
	v_mul_f32_e32 v109, 0x3d800000, v109
	v_mul_f32_e32 v110, 0x3d800000, v110
	v_mul_f32_e32 v111, 0x3d800000, v111
	v_mul_f32_e32 v112, 0x3d800000, v112
	v_mul_f32_e32 v113, 0x3d800000, v113
	v_mul_f32_e32 v114, 0x3d800000, v114
	v_mul_f32_e32 v115, 0x3d800000, v115
	v_mul_f32_e32 v116, 0x3d800000, v116
	v_mul_f32_e32 v117, 0x3d800000, v117
	v_mul_f32_e32 v118, 0x3d800000, v118
	v_mul_f32_e32 v119, 0x3d800000, v119
	v_mul_f32_e32 v120, 0x3d800000, v120
	v_mul_f32_e32 v121, 0x3d800000, v121

; #define LAS __attribute__((address_space(3)))
; __device__ __forceinline__ unsigned pk2(float lo, float hi) { return pg8::cvt_pk_bf16(lo, hi); }
; __device__ __forceinline__ void p0_transpose_item(const float* W, int K, int N, bf16_t* WT, int row_off, LAS float* scr, int item, int lane,
;                                                   const float* gain, int sc_lo, int sc_hi, float sc) {
;     ...
;     for (int i = 0; i < 8; ++i) {
;         const int kk = (lane >> 3) + 8 * i;
;         const float gm = gain ? gain[k0 + kk] : 1.0f;
;         LAS float* sp = scr + kk * 33 + 4 * (lane & 7);
;         sp[0] = wv[i][0] * gm; sp[1] = wv[i][1] * gm; sp[2] = wv[i][2] * gm; sp[3] = wv[i][3] * gm;
;     }
;     asm volatile("s_waitcnt lgkmcnt(0)" ::: "memory");
;     const int c = lane & 7;
; #pragma unroll
;     for (int j = 0; j < 4; ++j) {
;         const int n = (lane >> 3) + 8 * j; const LAS float* s = scr + (8 * c) * 33 + n;
;         const float mlt = (n0 + n >= sc_lo && n0 + n < sc_hi) ? sc : 1.0f;
;         u32x4 o; o.x = pk2(s[0 * 33] * mlt, s[1 * 33] * mlt); o.y = pk2(s[2 * 33] * mlt, s[3 * 33] * mlt);
;         o.z = pk2(s[4 * 33] * mlt, s[5 * 33] * mlt); o.w = pk2(s[6 * 33] * mlt, s[7 * 33] * mlt);
;         *(u32x4*)(WT + (size_t)(row_off + n0 + n) * K + k0 + 8 * c) = o;
;     }
.Lp0x_last_ir_B:
	s_waitcnt vmcnt(0)
	s_lshr_b32 s9, s42, 7
	s_mul_i32 s9, s9, 0xaaab
	s_lshr_b32 s9, s9, 17
	s_mul_i32 s12, s9, 0x180
	s_sub_i32 s12, s42, s12
	v_mul_f32_e32 v50, v50, v82
	v_mul_f32_e32 v51, v51, v82
	v_mul_f32_e32 v52, v52, v82
	v_mul_f32_e32 v53, v53, v82
	ds_write2_b32 v6, v50, v51 offset1:1
	ds_write2_b32 v6, v52, v53 offset0:2 offset1:3
	v_mul_f32_e32 v54, v54, v83
	v_mul_f32_e32 v55, v55, v83
	v_mul_f32_e32 v56, v56, v83
	v_mul_f32_e32 v57, v57, v83
	v_add_u32_e32 v0, 0x420, v6
	ds_write2_b32 v0, v54, v55 offset1:1
	ds_write2_b32 v0, v56, v57 offset0:2 offset1:3
	v_mul_f32_e32 v58, v58, v84
	v_mul_f32_e32 v59, v59, v84
	v_mul_f32_e32 v60, v60, v84
	v_mul_f32_e32 v61, v61, v84
	v_add_u32_e32 v0, 0x840, v6
	ds_write2_b32 v0, v58, v59 offset1:1
	ds_write2_b32 v0, v60, v61 offset0:2 offset1:3
	v_mul_f32_e32 v62, v62, v85
	v_mul_f32_e32 v63, v63, v85
	v_mul_f32_e32 v64, v64, v85
	v_mul_f32_e32 v65, v65, v85
	v_add_u32_e32 v0, 0xc60, v6
	ds_write2_b32 v0, v62, v63 offset1:1
	ds_write2_b32 v0, v64, v65 offset0:2 offset1:3
	v_mul_f32_e32 v66, v66, v86
	v_mul_f32_e32 v67, v67, v86
	v_mul_f32_e32 v68, v68, v86
	v_mul_f32_e32 v69, v69, v86
	v_add_u32_e32 v0, 0x1080, v6
	ds_write2_b32 v0, v66, v67 offset1:1
	ds_write2_b32 v0, v68, v69 offset0:2 offset1:3
	v_mul_f32_e32 v70, v70, v87
	v_mul_f32_e32 v71, v71, v87
	v_mul_f32_e32 v72, v72, v87
	v_mul_f32_e32 v73, v73, v87
	v_add_u32_e32 v0, 0x14a0, v6
	ds_write2_b32 v0, v70, v71 offset1:1
	ds_write2_b32 v0, v72, v73 offset0:2 offset1:3
	v_mul_f32_e32 v74, v74, v88
	v_mul_f32_e32 v75, v75, v88
	v_mul_f32_e32 v76, v76, v88
	v_mul_f32_e32 v77, v77, v88
	v_add_u32_e32 v0, 0x18c0, v6
	ds_write2_b32 v0, v74, v75 offset1:1
	ds_write2_b32 v0, v76, v77 offset0:2 offset1:3
	v_mul_f32_e32 v78, v78, v89
	v_mul_f32_e32 v79, v79, v89
	v_mul_f32_e32 v80, v80, v89
	v_mul_f32_e32 v81, v81, v89
	v_add_u32_e32 v0, 0x1ce0, v6
	ds_write2_b32 v0, v78, v79 offset1:1
	ds_write2_b32 v0, v80, v81 offset0:2 offset1:3
	s_waitcnt lgkmcnt(0)
	ds_read_b32 v90, v7 offset:0
	ds_read_b32 v91, v7 offset:132
	ds_read_b32 v92, v7 offset:264
	ds_read_b32 v93, v7 offset:396
	ds_read_b32 v94, v7 offset:528
	ds_read_b32 v95, v7 offset:660
	ds_read_b32 v96, v7 offset:792
	ds_read_b32 v97, v7 offset:924
	ds_read_b32 v98, v7 offset:32
	ds_read_b32 v99, v7 offset:164
	ds_read_b32 v100, v7 offset:296
	ds_read_b32 v101, v7 offset:428
	ds_read_b32 v102, v7 offset:560
	ds_read_b32 v103, v7 offset:692
	ds_read_b32 v104, v7 offset:824
	ds_read_b32 v105, v7 offset:956
	ds_read_b32 v106, v7 offset:64
	ds_read_b32 v107, v7 offset:196
	ds_read_b32 v108, v7 offset:328
	ds_read_b32 v109, v7 offset:460
	ds_read_b32 v110, v7 offset:592
	ds_read_b32 v111, v7 offset:724
	ds_read_b32 v112, v7 offset:856
	ds_read_b32 v113, v7 offset:988
	ds_read_b32 v114, v7 offset:96
	ds_read_b32 v115, v7 offset:228
	ds_read_b32 v116, v7 offset:360
	ds_read_b32 v117, v7 offset:492
	ds_read_b32 v118, v7 offset:624
	ds_read_b32 v119, v7 offset:756
	ds_read_b32 v120, v7 offset:888
	ds_read_b32 v121, v7 offset:1020
	s_sub_i32 s13, s12, 64
	s_cmp_lt_u32 s13, 64
	s_waitcnt lgkmcnt(0)
	s_cbranch_scc0 .Lp0x_nm_ir_tB
	v_mul_f32_e32 v90, 0x3d800000, v90
	v_mul_f32_e32 v91, 0x3d800000, v91
	v_mul_f32_e32 v92, 0x3d800000, v92
	v_mul_f32_e32 v93, 0x3d800000, v93
	v_mul_f32_e32 v94, 0x3d800000, v94
	v_mul_f32_e32 v95, 0x3d800000, v95
	v_mul_f32_e32 v96, 0x3d800000, v96
	v_mul_f32_e32 v97, 0x3d800000, v97
	v_mul_f32_e32 v98, 0x3d800000, v98
	v_mul_f32_e32 v99, 0x3d800000, v99
	v_mul_f32_e32 v100, 0x3d800000, v100
	v_mul_f32_e32 v101, 0x3d800000, v101
	v_mul_f32_e32 v102, 0x3d800000, v102
	v_mul_f32_e32 v103, 0x3d800000, v103
	v_mul_f32_e32 v104, 0x3d800000, v104
	v_mul_f32_e32 v105, 0x3d800000, v105
	v_mul_f32_e32 v106, 0x3d800000, v106
	v_mul_f32_e32 v107, 0x3d800000, v107
	v_mul_f32_e32 v108, 0x3d800000, v108
	v_mul_f32_e32 v109, 0x3d800000, v109
	v_mul_f32_e32 v110, 0x3d800000, v110
	v_mul_f32_e32 v111, 0x3d800000, v111
	v_mul_f32_e32 v112, 0x3d800000, v112
	v_mul_f32_e32 v113, 0x3d800000, v113
	v_mul_f32_e32 v114, 0x3d800000, v114
	v_mul_f32_e32 v115, 0x3d800000, v115
	v_mul_f32_e32 v116, 0x3d800000, v116
	v_mul_f32_e32 v117, 0x3d800000, v117
	v_mul_f32_e32 v118, 0x3d800000, v118
	v_mul_f32_e32 v119, 0x3d800000, v119
	v_mul_f32_e32 v120, 0x3d800000, v120
	v_mul_f32_e32 v121, 0x3d800000, v121
.Lp0x_nm_ir_tB:
	s_mul_i32 s34, s12, 0x20000
	s_lshl_b32 s35, s9, 7
	s_add_i32 s34, s34, s35
	s_add_u32 s40, s30, s34
	s_addc_u32 s41, s31, 0
	v_cvt_pk_bf16_f32 v122, v90, v91
	v_cvt_pk_bf16_f32 v123, v92, v93
	v_cvt_pk_bf16_f32 v124, v94, v95
	v_cvt_pk_bf16_f32 v125, v96, v97
	global_store_dwordx4 v8, v[122:125], s[40:41]
	s_add_u32 s40, s40, 0x8000
	s_addc_u32 s41, s41, 0
	v_cvt_pk_bf16_f32 v126, v98, v99
	v_cvt_pk_bf16_f32 v127, v100, v101
	v_cvt_pk_bf16_f32 v128, v102, v103
	v_cvt_pk_bf16_f32 v129, v104, v105
	global_store_dwordx4 v8, v[126:129], s[40:41]
	s_add_u32 s40, s40, 0x8000
	s_addc_u32 s41, s41, 0
	v_cvt_pk_bf16_f32 v130, v106, v107
	v_cvt_pk_bf16_f32 v131, v108, v109
	v_cvt_pk_bf16_f32 v132, v110, v111
	v_cvt_pk_bf16_f32 v133, v112, v113
	global_store_dwordx4 v8, v[130:133], s[40:41]
	s_add_u32 s40, s40, 0x8000
	s_addc_u32 s41, s41, 0
	v_cvt_pk_bf16_f32 v134, v114, v115
	v_cvt_pk_bf16_f32 v135, v116, v117
	v_cvt_pk_bf16_f32 v136, v118, v119
	v_cvt_pk_bf16_f32 v137, v120, v121
	global_store_dwordx4 v8, v[134:137], s[40:41]

; #define LAS __attribute__((address_space(3)))
; #define SEG(cnt, ...) if (r < (cnt)) { p0_transpose_item(__VA_ARGS__); continue; } r -= (cnt);
; __device__ __forceinline__ void p0_transpose_item(const float* W, int K, int N, bf16_t* WT, int row_off, LAS float* scr, int item, int lane,
;                                                   const float* gain, int sc_lo, int sc_hi, float sc) {
;     const int nblk = N / 32, kb = item / nblk, nb = item % nblk, k0 = 64 * kb, n0 = 32 * nb;
;     f32x4 wv[8];
; #pragma unroll
;     for (int i = 0; i < 8; ++i) wv[i] = *(const f32x4*)(W + (size_t)(k0 + (lane >> 3) + 8 * i) * N + n0 + 4 * (lane & 7));
; #pragma unroll
;     for (int i = 0; i < 8; ++i) {
;         const int kk = (lane >> 3) + 8 * i;
;         const float gm = gain ? gain[k0 + kk] : 1.0f;
;         LAS float* sp = scr + kk * 33 + 4 * (lane & 7);
;         sp[0] = wv[i][0] * gm; sp[1] = wv[i][1] * gm; sp[2] = wv[i][2] * gm; sp[3] = wv[i][3] * gm;
;     }
;     asm volatile("s_waitcnt lgkmcnt(0)" ::: "memory");
; __global__ void __launch_bounds__(NTHREADS, 2) hybrid_fwd(Params P) {
;     ...
;             SEG(5376, w_in_even + (size_t)2048 * EIN, 2048, EIN, WinE + (size_t)EIN * 2048, 0, scr, r, lane, norm_mix + 2 * 2048, 0, 0, 1.f)
.Lp0x_l1:
	s_load_dwordx2 s[26:27], s[96:97], 0x48
	s_load_dwordx2 s[28:29], s[96:97], 0x40
	v_readlane_b32 s30, v254, 42
	v_readlane_b32 s31, v254, 43
	v_mul_u32_u24_e32 v4, 0x5400, v2
	v_lshl_add_u32 v4, v3, 4, v4
	v_mul_u32_u24_e32 v8, 0x1000, v2
	v_lshl_add_u32 v8, v3, 4, v8
	s_mov_b32 s6, s43
	s_waitcnt lgkmcnt(0)
	s_add_u32 s26, s26, 0x2a00000
	s_addc_u32 s27, s27, 0
	s_add_u32 s28, s28, 0x4000
	s_addc_u32 s29, s29, 0
	s_add_u32 s30, s30, 0x1500000
	s_addc_u32 s31, s31, 0
	s_cmpk_ge_i32 s6, 0x1500
	s_cbranch_scc1 .Lp0x_done_ie
	s_lshr_b32 s9, s6, 3
	s_mul_i32 s9, s9, 0xc31
	s_lshr_b32 s9, s9, 16
	s_mul_i32 s12, s9, 0xa8
	s_sub_i32 s12, s6, s12
	s_mul_i32 s13, s9, 0x150000
	s_lshl_b32 s34, s12, 7
	s_add_i32 s13, s13, s34
	s_add_u32 s36, s26, s13
	s_addc_u32 s37, s27, 0
	global_load_dwordx4 v[10:13], v4, s[36:37]
	s_add_u32 s36, s36, 0x2a000
	s_addc_u32 s37, s37, 0
	global_load_dwordx4 v[14:17], v4, s[36:37]
	s_add_u32 s36, s36, 0x2a000
	s_addc_u32 s37, s37, 0
	global_load_dwordx4 v[18:21], v4, s[36:37]
	s_add_u32 s36, s36, 0x2a000
	s_addc_u32 s37, s37, 0
	global_load_dwordx4 v[22:25], v4, s[36:37]
	s_add_u32 s36, s36, 0x2a000
	s_addc_u32 s37, s37, 0
	global_load_dwordx4 v[26:29], v4, s[36:37]
	s_add_u32 s36, s36, 0x2a000
	s_addc_u32 s37, s37, 0
	global_load_dwordx4 v[30:33], v4, s[36:37]
	s_add_u32 s36, s36, 0x2a000
	s_addc_u32 s37, s37, 0
	global_load_dwordx4 v[34:37], v4, s[36:37]
	s_add_u32 s36, s36, 0x2a000
	s_addc_u32 s37, s37, 0
	global_load_dwordx4 v[38:41], v4, s[36:37]
	s_lshl_b32 s34, s9, 8
	s_add_u32 s38, s28, s34
	s_addc_u32 s39, s29, 0
	global_load_dword v42, v5, s[38:39]
	global_load_dword v43, v5, s[38:39] offset:32
	global_load_dword v44, v5, s[38:39] offset:64
	global_load_dword v45, v5, s[38:39] offset:96
	global_load_dword v46, v5, s[38:39] offset:128
	global_load_dword v47, v5, s[38:39] offset:160
	global_load_dword v48, v5, s[38:39] offset:192
	global_load_dword v49, v5, s[38:39] offset:224
.Lp0x_loop_ie:
	s_add_i32 s42, s6, s7
	s_cmpk_ge_i32 s42, 0x1500
	s_cbranch_scc1 .Lp0x_last_ie_A
	s_lshr_b32 s9, s42, 3
	s_mul_i32 s9, s9, 0xc31
	s_lshr_b32 s9, s9, 16
	s_mul_i32 s12, s9, 0xa8
	s_sub_i32 s12, s42, s12
	s_mul_i32 s13, s9, 0x150000
	s_lshl_b32 s34, s12, 7
	s_add_i32 s13, s13, s34
	s_add_u32 s36, s26, s13
	s_addc_u32 s37, s27, 0
	global_load_dwordx4 v[50:53], v4, s[36:37]
	s_add_u32 s36, s36, 0x2a000
	s_addc_u32 s37, s37, 0
	global_load_dwordx4 v[54:57], v4, s[36:37]
	s_add_u32 s36, s36, 0x2a000
	s_addc_u32 s37, s37, 0
	global_load_dwordx4 v[58:61], v4, s[36:37]
	s_add_u32 s36, s36, 0x2a000
	s_addc_u32 s37, s37, 0
	global_load_dwordx4 v[62:65], v4, s[36:37]
	s_add_u32 s36, s36, 0x2a000
	s_addc_u32 s37, s37, 0
	global_load_dwordx4 v[66:69], v4, s[36:37]
	s_add_u32 s36, s36, 0x2a000
	s_addc_u32 s37, s37, 0
	global_load_dwordx4 v[70:73], v4, s[36:37]
	s_add_u32 s36, s36, 0x2a000
	s_addc_u32 s37, s37, 0
	global_load_dwordx4 v[74:77], v4, s[36:37]
	s_add_u32 s36, s36, 0x2a000
	s_addc_u32 s37, s37, 0
	global_load_dwordx4 v[78:81], v4, s[36:37]
	s_lshl_b32 s34, s9, 8
	s_add_u32 s38, s28, s34
	s_addc_u32 s39, s29, 0
	global_load_dword v82, v5, s[38:39]
	global_load_dword v83, v5, s[38:39] offset:32
	global_load_dword v84, v5, s[38:39] offset:64
	global_load_dword v85, v5, s[38:39] offset:96
	global_load_dword v86, v5, s[38:39] offset:128
	global_load_dword v87, v5, s[38:39] offset:160
	global_load_dword v88, v5, s[38:39] offset:192
	global_load_dword v89, v5, s[38:39] offset:224
	s_waitcnt vmcnt(16)
	s_lshr_b32 s9, s6, 3
	s_mul_i32 s9, s9, 0xc31
	s_lshr_b32 s9, s9, 16
	s_mul_i32 s12, s9, 0xa8
	s_sub_i32 s12, s6, s12
	v_mul_f32_e32 v10, v10, v42
	v_mul_f32_e32 v11, v11, v42
	v_mul_f32_e32 v12, v12, v42
	v_mul_f32_e32 v13, v13, v42
	ds_write2_b32 v6, v10, v11 offset1:1
	ds_write2_b32 v6, v12, v13 offset0:2 offset1:3
	v_mul_f32_e32 v14, v14, v43
	v_mul_f32_e32 v15, v15, v43
	v_mul_f32_e32 v16, v16, v43
	v_mul_f32_e32 v17, v17, v43
	v_add_u32_e32 v0, 0x420, v6
	ds_write2_b32 v0, v14, v15 offset1:1
	ds_write2_b32 v0, v16, v17 offset0:2 offset1:3
	v_mul_f32_e32 v18, v18, v44
	v_mul_f32_e32 v19, v19, v44
	v_mul_f32_e32 v20, v20, v44
	v_mul_f32_e32 v21, v21, v44
	v_add_u32_e32 v0, 0x840, v6
	ds_write2_b32 v0, v18, v19 offset1:1
	ds_write2_b32 v0, v20, v21 offset0:2 offset1:3
	v_mul_f32_e32 v22, v22, v45
	v_mul_f32_e32 v23, v23, v45
	v_mul_f32_e32 v24, v24, v45
	v_mul_f32_e32 v25, v25, v45
	v_add_u32_e32 v0, 0xc60, v6
	ds_write2_b32 v0, v22, v23 offset1:1
	ds_write2_b32 v0, v24, v25 offset0:2 offset1:3
	v_mul_f32_e32 v26, v26, v46
	v_mul_f32_e32 v27, v27, v46
	v_mul_f32_e32 v28, v28, v46
	v_mul_f32_e32 v29, v29, v46
	v_add_u32_e32 v0, 0x1080, v6
	ds_write2_b32 v0, v26, v27 offset1:1
	ds_write2_b32 v0, v28, v29 offset0:2 offset1:3
	v_mul_f32_e32 v30, v30, v47
	v_mul_f32_e32 v31, v31, v47
	v_mul_f32_e32 v32, v32, v47
	v_mul_f32_e32 v33, v33, v47
	v_add_u32_e32 v0, 0x14a0, v6
	ds_write2_b32 v0, v30, v31 offset1:1
	ds_write2_b32 v0, v32, v33 offset0:2 offset1:3
	v_mul_f32_e32 v34, v34, v48
	v_mul_f32_e32 v35, v35, v48
	v_mul_f32_e32 v36, v36, v48
	v_mul_f32_e32 v37, v37, v48
	v_add_u32_e32 v0, 0x18c0, v6
	ds_write2_b32 v0, v34, v35 offset1:1
	ds_write2_b32 v0, v36, v37 offset0:2 offset1:3
	v_mul_f32_e32 v38, v38, v49
	v_mul_f32_e32 v39, v39, v49
	v_mul_f32_e32 v40, v40, v49
	v_mul_f32_e32 v41, v41, v49
	v_add_u32_e32 v0, 0x1ce0, v6
	ds_write2_b32 v0, v38, v39 offset1:1
	ds_write2_b32 v0, v40, v41 offset0:2 offset1:3
	s_waitcnt lgkmcnt(0)
; #define LAS __attribute__((address_space(3)))
; __device__ __forceinline__ unsigned pk2(float lo, float hi) { return pg8::cvt_pk_bf16(lo, hi); }
; __device__ __forceinline__ void p0_transpose_item(const float* W, int K, int N, bf16_t* WT, int row_off, LAS float* scr, int item, int lane,
;                                                   const float* gain, int sc_lo, int sc_hi, float sc) {
;     ...
;     for (int i = 0; i < 8; ++i) {
;         const int kk = (lane >> 3) + 8 * i;
;         const float gm = gain ? gain[k0 + kk] : 1.0f;
;         LAS float* sp = scr + kk * 33 + 4 * (lane & 7);
;         sp[0] = wv[i][0] * gm; sp[1] = wv[i][1] * gm; sp[2] = wv[i][2] * gm; sp[3] = wv[i][3] * gm;
;     }
;     asm volatile("s_waitcnt lgkmcnt(0)" ::: "memory");
;     const int c = lane & 7;
; #pragma unroll
;     for (int j = 0; j < 4; ++j) {
;         const int n = (lane >> 3) + 8 * j; const LAS float* s = scr + (8 * c) * 33 + n;
;         const float mlt = (n0 + n >= sc_lo && n0 + n < sc_hi) ? sc : 1.0f;
;         u32x4 o; o.x = pk2(s[0 * 33] * mlt, s[1 * 33] * mlt); o.y = pk2(s[2 * 33] * mlt, s[3 * 33] * mlt);
;         o.z = pk2(s[4 * 33] * mlt, s[5 * 33] * mlt); o.w = pk2(s[6 * 33] * mlt, s[7 * 33] * mlt);
;         *(u32x4*)(WT + (size_t)(row_off + n0 + n) * K + k0 + 8 * c) = o;
;     }
	ds_read_b32 v90, v7 offset:0
	ds_read_b32 v91, v7 offset:132
	ds_read_b32 v92, v7 offset:264
	ds_read_b32 v93, v7 offset:396
	ds_read_b32 v94, v7 offset:528
	ds_read_b32 v95, v7 offset:660
	ds_read_b32 v96, v7 offset:792
	ds_read_b32 v97, v7 offset:924
	ds_read_b32 v98, v7 offset:32
	ds_read_b32 v99, v7 offset:164
	ds_read_b32 v100, v7 offset:296
	ds_read_b32 v101, v7 offset:428
	ds_read_b32 v102, v7 offset:560
	ds_read_b32 v103, v7 offset:692
	ds_read_b32 v104, v7 offset:824
	ds_read_b32 v105, v7 offset:956
	ds_read_b32 v106, v7 offset:64
	ds_read_b32 v107, v7 offset:196
	ds_read_b32 v108, v7 offset:328
	ds_read_b32 v109, v7 offset:460
	ds_read_b32 v110, v7 offset:592
	ds_read_b32 v111, v7 offset:724
	ds_read_b32 v112, v7 offset:856
	ds_read_b32 v113, v7 offset:988
	ds_read_b32 v114, v7 offset:96
	ds_read_b32 v115, v7 offset:228
	ds_read_b32 v116, v7 offset:360
	ds_read_b32 v117, v7 offset:492
	ds_read_b32 v118, v7 offset:624
	ds_read_b32 v119, v7 offset:756
	ds_read_b32 v120, v7 offset:888
	ds_read_b32 v121, v7 offset:1020
	s_waitcnt lgkmcnt(0)
	s_mul_i32 s34, s12, 0x20000
	s_lshl_b32 s35, s9, 7
	s_add_i32 s34, s34, s35
	s_add_u32 s40, s30, s34
	s_addc_u32 s41, s31, 0
	v_cvt_pk_bf16_f32 v122, v90, v91
	v_cvt_pk_bf16_f32 v123, v92, v93
	v_cvt_pk_bf16_f32 v124, v94, v95
	v_cvt_pk_bf16_f32 v125, v96, v97
	global_store_dwordx4 v8, v[122:125], s[40:41]
	s_add_u32 s40, s40, 0x8000
	s_addc_u32 s41, s41, 0
	v_cvt_pk_bf16_f32 v126, v98, v99
	v_cvt_pk_bf16_f32 v127, v100, v101
	v_cvt_pk_bf16_f32 v128, v102, v103
	v_cvt_pk_bf16_f32 v129, v104, v105
	global_store_dwordx4 v8, v[126:129], s[40:41]
	s_add_u32 s40, s40, 0x8000
	s_addc_u32 s41, s41, 0
	v_cvt_pk_bf16_f32 v130, v106, v107
	v_cvt_pk_bf16_f32 v131, v108, v109
	v_cvt_pk_bf16_f32 v132, v110, v111
	v_cvt_pk_bf16_f32 v133, v112, v113
	global_store_dwordx4 v8, v[130:133], s[40:41]
	s_add_u32 s40, s40, 0x8000
	s_addc_u32 s41, s41, 0
	v_cvt_pk_bf16_f32 v134, v114, v115
	v_cvt_pk_bf16_f32 v135, v116, v117
	v_cvt_pk_bf16_f32 v136, v118, v119
	v_cvt_pk_bf16_f32 v137, v120, v121
	global_store_dwordx4 v8, v[134:137], s[40:41]
	s_add_i32 s6, s42, s7
	s_cmpk_ge_i32 s6, 0x1500
	s_cbranch_scc1 .Lp0x_last_ie_B
	s_lshr_b32 s9, s6, 3
	s_mul_i32 s9, s9, 0xc31
	s_lshr_b32 s9, s9, 16
	s_mul_i32 s12, s9, 0xa8
	s_sub_i32 s12, s6, s12
	s_mul_i32 s13, s9, 0x150000
	s_lshl_b32 s34, s12, 7
	s_add_i32 s13, s13, s34
	s_add_u32 s36, s26, s13
	s_addc_u32 s37, s27, 0
	global_load_dwordx4 v[10:13], v4, s[36:37]
	s_add_u32 s36, s36, 0x2a000
	s_addc_u32 s37, s37, 0
	global_load_dwordx4 v[14:17], v4, s[36:37]
	s_add_u32 s36, s36, 0x2a000
	s_addc_u32 s37, s37, 0
	global_load_dwordx4 v[18:21], v4, s[36:37]
	s_add_u32 s36, s36, 0x2a000
	s_addc_u32 s37, s37, 0
	global_load_dwordx4 v[22:25], v4, s[36:37]
	s_add_u32 s36, s36, 0x2a000
	s_addc_u32 s37, s37, 0
	global_load_dwordx4 v[26:29], v4, s[36:37]
	s_add_u32 s36, s36, 0x2a000
	s_addc_u32 s37, s37, 0
	global_load_dwordx4 v[30:33], v4, s[36:37]
	s_add_u32 s36, s36, 0x2a000
	s_addc_u32 s37, s37, 0
	global_load_dwordx4 v[34:37], v4, s[36:37]
	s_add_u32 s36, s36, 0x2a000
	s_addc_u32 s37, s37, 0
	global_load_dwordx4 v[38:41], v4, s[36:37]
	s_lshl_b32 s34, s9, 8
	s_add_u32 s38, s28, s34
	s_addc_u32 s39, s29, 0
	global_load_dword v42, v5, s[38:39]
	global_load_dword v43, v5, s[38:39] offset:32
	global_load_dword v44, v5, s[38:39] offset:64
	global_load_dword v45, v5, s[38:39] offset:96
	global_load_dword v46, v5, s[38:39] offset:128
	global_load_dword v47, v5, s[38:39] offset:160
	global_load_dword v48, v5, s[38:39] offset:192
	global_load_dword v49, v5, s[38:39] offset:224
	s_waitcnt vmcnt(16)
	s_lshr_b32 s9, s42, 3
	s_mul_i32 s9, s9, 0xc31
	s_lshr_b32 s9, s9, 16
	s_mul_i32 s12, s9, 0xa8
	s_sub_i32 s12, s42, s12
	v_mul_f32_e32 v50, v50, v82
	v_mul_f32_e32 v51, v51, v82
	v_mul_f32_e32 v52, v52, v82
	v_mul_f32_e32 v53, v53, v82
	ds_write2_b32 v6, v50, v51 offset1:1
	ds_write2_b32 v6, v52, v53 offset0:2 offset1:3
	v_mul_f32_e32 v54, v54, v83
	v_mul_f32_e32 v55, v55, v83
	v_mul_f32_e32 v56, v56, v83
	v_mul_f32_e32 v57, v57, v83
	v_add_u32_e32 v0, 0x420, v6
	ds_write2_b32 v0, v54, v55 offset1:1
	ds_write2_b32 v0, v56, v57 offset0:2 offset1:3
	v_mul_f32_e32 v58, v58, v84
	v_mul_f32_e32 v59, v59, v84
	v_mul_f32_e32 v60, v60, v84
	v_mul_f32_e32 v61, v61, v84
	v_add_u32_e32 v0, 0x840, v6
	ds_write2_b32 v0, v58, v59 offset1:1
	ds_write2_b32 v0, v60, v61 offset0:2 offset1:3
	v_mul_f32_e32 v62, v62, v85
	v_mul_f32_e32 v63, v63, v85
	v_mul_f32_e32 v64, v64, v85
	v_mul_f32_e32 v65, v65, v85
	v_add_u32_e32 v0, 0xc60, v6
	ds_write2_b32 v0, v62, v63 offset1:1
	ds_write2_b32 v0, v64, v65 offset0:2 offset1:3
	v_mul_f32_e32 v66, v66, v86
	v_mul_f32_e32 v67, v67, v86
	v_mul_f32_e32 v68, v68, v86
	v_mul_f32_e32 v69, v69, v86
	v_add_u32_e32 v0, 0x1080, v6
	ds_write2_b32 v0, v66, v67 offset1:1
	ds_write2_b32 v0, v68, v69 offset0:2 offset1:3
	v_mul_f32_e32 v70, v70, v87
	v_mul_f32_e32 v71, v71, v87
	v_mul_f32_e32 v72, v72, v87
	v_mul_f32_e32 v73, v73, v87
	v_add_u32_e32 v0, 0x14a0, v6
	ds_write2_b32 v0, v70, v71 offset1:1
	ds_write2_b32 v0, v72, v73 offset0:2 offset1:3
	v_mul_f32_e32 v74, v74, v88
	v_mul_f32_e32 v75, v75, v88
	v_mul_f32_e32 v76, v76, v88
	v_mul_f32_e32 v77, v77, v88
	v_add_u32_e32 v0, 0x18c0, v6
	ds_write2_b32 v0, v74, v75 offset1:1
	ds_write2_b32 v0, v76, v77 offset0:2 offset1:3
	v_mul_f32_e32 v78, v78, v89
	v_mul_f32_e32 v79, v79, v89
	v_mul_f32_e32 v80, v80, v89
	v_mul_f32_e32 v81, v81, v89
	v_add_u32_e32 v0, 0x1ce0, v6
	ds_write2_b32 v0, v78, v79 offset1:1
	ds_write2_b32 v0, v80, v81 offset0:2 offset1:3
	s_waitcnt lgkmcnt(0)
; #define LAS __attribute__((address_space(3)))
; __device__ __forceinline__ unsigned pk2(float lo, float hi) { return pg8::cvt_pk_bf16(lo, hi); }
; __device__ __forceinline__ void p0_transpose_item(const float* W, int K, int N, bf16_t* WT, int row_off, LAS float* scr, int item, int lane,
;                                                   const float* gain, int sc_lo, int sc_hi, float sc) {
;     ...
;     for (int i = 0; i < 8; ++i) {
;         const int kk = (lane >> 3) + 8 * i;
;         const float gm = gain ? gain[k0 + kk] : 1.0f;
;         LAS float* sp = scr + kk * 33 + 4 * (lane & 7);
;         sp[0] = wv[i][0] * gm; sp[1] = wv[i][1] * gm; sp[2] = wv[i][2] * gm; sp[3] = wv[i][3] * gm;
;     }
;     asm volatile("s_waitcnt lgkmcnt(0)" ::: "memory");
;     const int c = lane & 7;
; #pragma unroll
;     for (int j = 0; j < 4; ++j) {
;         const int n = (lane >> 3) + 8 * j; const LAS float* s = scr + (8 * c) * 33 + n;
;         const float mlt = (n0 + n >= sc_lo && n0 + n < sc_hi) ? sc : 1.0f;
;         u32x4 o; o.x = pk2(s[0 * 33] * mlt, s[1 * 33] * mlt); o.y = pk2(s[2 * 33] * mlt, s[3 * 33] * mlt);
;         o.z = pk2(s[4 * 33] * mlt, s[5 * 33] * mlt); o.w = pk2(s[6 * 33] * mlt, s[7 * 33] * mlt);
;         *(u32x4*)(WT + (size_t)(row_off + n0 + n) * K + k0 + 8 * c) = o;
;     }
	ds_read_b32 v90, v7 offset:0
	ds_read_b32 v91, v7 offset:132
	ds_read_b32 v92, v7 offset:264
	ds_read_b32 v93, v7 offset:396
	ds_read_b32 v94, v7 offset:528
	ds_read_b32 v95, v7 offset:660
	ds_read_b32 v96, v7 offset:792
	ds_read_b32 v97, v7 offset:924
	ds_read_b32 v98, v7 offset:32
	ds_read_b32 v99, v7 offset:164
	ds_read_b32 v100, v7 offset:296
	ds_read_b32 v101, v7 offset:428
	ds_read_b32 v102, v7 offset:560
	ds_read_b32 v103, v7 offset:692
	ds_read_b32 v104, v7 offset:824
	ds_read_b32 v105, v7 offset:956
	ds_read_b32 v106, v7 offset:64
	ds_read_b32 v107, v7 offset:196
	ds_read_b32 v108, v7 offset:328
	ds_read_b32 v109, v7 offset:460
	ds_read_b32 v110, v7 offset:592
	ds_read_b32 v111, v7 offset:724
	ds_read_b32 v112, v7 offset:856
	ds_read_b32 v113, v7 offset:988
	ds_read_b32 v114, v7 offset:96
	ds_read_b32 v115, v7 offset:228
	ds_read_b32 v116, v7 offset:360
	ds_read_b32 v117, v7 offset:492
	ds_read_b32 v118, v7 offset:624
	ds_read_b32 v119, v7 offset:756
	ds_read_b32 v120, v7 offset:888
	ds_read_b32 v121, v7 offset:1020
	s_waitcnt lgkmcnt(0)
	s_mul_i32 s34, s12, 0x20000
	s_lshl_b32 s35, s9, 7
	s_add_i32 s34, s34, s35
	s_add_u32 s40, s30, s34
	s_addc_u32 s41, s31, 0
	v_cvt_pk_bf16_f32 v122, v90, v91
	v_cvt_pk_bf16_f32 v123, v92, v93
	v_cvt_pk_bf16_f32 v124, v94, v95
	v_cvt_pk_bf16_f32 v125, v96, v97
	global_store_dwordx4 v8, v[122:125], s[40:41]
	s_add_u32 s40, s40, 0x8000
	s_addc_u32 s41, s41, 0
	v_cvt_pk_bf16_f32 v126, v98, v99
	v_cvt_pk_bf16_f32 v127, v100, v101
	v_cvt_pk_bf16_f32 v128, v102, v103
	v_cvt_pk_bf16_f32 v129, v104, v105
	global_store_dwordx4 v8, v[126:129], s[40:41]
	s_add_u32 s40, s40, 0x8000
	s_addc_u32 s41, s41, 0
	v_cvt_pk_bf16_f32 v130, v106, v107
	v_cvt_pk_bf16_f32 v131, v108, v109
	v_cvt_pk_bf16_f32 v132, v110, v111
	v_cvt_pk_bf16_f32 v133, v112, v113
	global_store_dwordx4 v8, v[130:133], s[40:41]
	s_add_u32 s40, s40, 0x8000
	s_addc_u32 s41, s41, 0
	v_cvt_pk_bf16_f32 v134, v114, v115
	v_cvt_pk_bf16_f32 v135, v116, v117
	v_cvt_pk_bf16_f32 v136, v118, v119
	v_cvt_pk_bf16_f32 v137, v120, v121
	global_store_dwordx4 v8, v[134:137], s[40:41]
	s_branch .Lp0x_loop_ie
.Lp0x_last_ie_A:
	s_waitcnt vmcnt(0)
	s_lshr_b32 s9, s6, 3
	s_mul_i32 s9, s9, 0xc31
	s_lshr_b32 s9, s9, 16
	s_mul_i32 s12, s9, 0xa8
	s_sub_i32 s12, s6, s12
	v_mul_f32_e32 v10, v10, v42
	v_mul_f32_e32 v11, v11, v42
	v_mul_f32_e32 v12, v12, v42
	v_mul_f32_e32 v13, v13, v42
	ds_write2_b32 v6, v10, v11 offset1:1
	ds_write2_b32 v6, v12, v13 offset0:2 offset1:3
	v_mul_f32_e32 v14, v14, v43
	v_mul_f32_e32 v15, v15, v43
	v_mul_f32_e32 v16, v16, v43
	v_mul_f32_e32 v17, v17, v43
	v_add_u32_e32 v0, 0x420, v6
	ds_write2_b32 v0, v14, v15 offset1:1
	ds_write2_b32 v0, v16, v17 offset0:2 offset1:3
	v_mul_f32_e32 v18, v18, v44
	v_mul_f32_e32 v19, v19, v44
	v_mul_f32_e32 v20, v20, v44
	v_mul_f32_e32 v21, v21, v44
	v_add_u32_e32 v0, 0x840, v6
	ds_write2_b32 v0, v18, v19 offset1:1
	ds_write2_b32 v0, v20, v21 offset0:2 offset1:3
	v_mul_f32_e32 v22, v22, v45
	v_mul_f32_e32 v23, v23, v45
	v_mul_f32_e32 v24, v24, v45
	v_mul_f32_e32 v25, v25, v45
	v_add_u32_e32 v0, 0xc60, v6
	ds_write2_b32 v0, v22, v23 offset1:1
	ds_write2_b32 v0, v24, v25 offset0:2 offset1:3
	v_mul_f32_e32 v26, v26, v46
	v_mul_f32_e32 v27, v27, v46
	v_mul_f32_e32 v28, v28, v46
	v_mul_f32_e32 v29, v29, v46
	v_add_u32_e32 v0, 0x1080, v6
	ds_write2_b32 v0, v26, v27 offset1:1
	ds_write2_b32 v0, v28, v29 offset0:2 offset1:3
	v_mul_f32_e32 v30, v30, v47
	v_mul_f32_e32 v31, v31, v47
	v_mul_f32_e32 v32, v32, v47
	v_mul_f32_e32 v33, v33, v47
	v_add_u32_e32 v0, 0x14a0, v6
	ds_write2_b32 v0, v30, v31 offset1:1
	ds_write2_b32 v0, v32, v33 offset0:2 offset1:3
	v_mul_f32_e32 v34, v34, v48
	v_mul_f32_e32 v35, v35, v48
	v_mul_f32_e32 v36, v36, v48
	v_mul_f32_e32 v37, v37, v48
	v_add_u32_e32 v0, 0x18c0, v6
	ds_write2_b32 v0, v34, v35 offset1:1
	ds_write2_b32 v0, v36, v37 offset0:2 offset1:3
	v_mul_f32_e32 v38, v38, v49
	v_mul_f32_e32 v39, v39, v49
	v_mul_f32_e32 v40, v40, v49
	v_mul_f32_e32 v41, v41, v49
	v_add_u32_e32 v0, 0x1ce0, v6
	ds_write2_b32 v0, v38, v39 offset1:1
	ds_write2_b32 v0, v40, v41 offset0:2 offset1:3
	s_waitcnt lgkmcnt(0)
	ds_read_b32 v90, v7 offset:0
	ds_read_b32 v91, v7 offset:132
	ds_read_b32 v92, v7 offset:264
	ds_read_b32 v93, v7 offset:396
	ds_read_b32 v94, v7 offset:528
	ds_read_b32 v95, v7 offset:660
	ds_read_b32 v96, v7 offset:792
	ds_read_b32 v97, v7 offset:924
	ds_read_b32 v98, v7 offset:32
	ds_read_b32 v99, v7 offset:164
	ds_read_b32 v100, v7 offset:296
	ds_read_b32 v101, v7 offset:428
	ds_read_b32 v102, v7 offset:560
	ds_read_b32 v103, v7 offset:692
	ds_read_b32 v104, v7 offset:824
	ds_read_b32 v105, v7 offset:956
	ds_read_b32 v106, v7 offset:64
	ds_read_b32 v107, v7 offset:196
	ds_read_b32 v108, v7 offset:328
	ds_read_b32 v109, v7 offset:460
	ds_read_b32 v110, v7 offset:592
	ds_read_b32 v111, v7 offset:724
	ds_read_b32 v112, v7 offset:856
	ds_read_b32 v113, v7 offset:988
	ds_read_b32 v114, v7 offset:96
	ds_read_b32 v115, v7 offset:228
	ds_read_b32 v116, v7 offset:360
	ds_read_b32 v117, v7 offset:492
	ds_read_b32 v118, v7 offset:624
	ds_read_b32 v119, v7 offset:756
	ds_read_b32 v120, v7 offset:888
	ds_read_b32 v121, v7 offset:1020
	s_waitcnt lgkmcnt(0)
	s_mul_i32 s34, s12, 0x20000
	s_lshl_b32 s35, s9, 7
	s_add_i32 s34, s34, s35
	s_add_u32 s40, s30, s34
	s_addc_u32 s41, s31, 0
	v_cvt_pk_bf16_f32 v122, v90, v91
	v_cvt_pk_bf16_f32 v123, v92, v93
	v_cvt_pk_bf16_f32 v124, v94, v95
	v_cvt_pk_bf16_f32 v125, v96, v97
	global_store_dwordx4 v8, v[122:125], s[40:41]
	s_add_u32 s40, s40, 0x8000
	s_addc_u32 s41, s41, 0
	v_cvt_pk_bf16_f32 v126, v98, v99
	v_cvt_pk_bf16_f32 v127, v100, v101
	v_cvt_pk_bf16_f32 v128, v102, v103
	v_cvt_pk_bf16_f32 v129, v104, v105
	global_store_dwordx4 v8, v[126:129], s[40:41]
	s_add_u32 s40, s40, 0x8000
	s_addc_u32 s41, s41, 0
	v_cvt_pk_bf16_f32 v130, v106, v107
	v_cvt_pk_bf16_f32 v131, v108, v109
	v_cvt_pk_bf16_f32 v132, v110, v111
	v_cvt_pk_bf16_f32 v133, v112, v113
	global_store_dwordx4 v8, v[130:133], s[40:41]
	s_add_u32 s40, s40, 0x8000
	s_addc_u32 s41, s41, 0
	v_cvt_pk_bf16_f32 v134, v114, v115
	v_cvt_pk_bf16_f32 v135, v116, v117
	v_cvt_pk_bf16_f32 v136, v118, v119
	v_cvt_pk_bf16_f32 v137, v120, v121
	global_store_dwordx4 v8, v[134:137], s[40:41]
	s_branch .Lp0x_done_ie
; #define LAS __attribute__((address_space(3)))
; __device__ __forceinline__ unsigned pk2(float lo, float hi) { return pg8::cvt_pk_bf16(lo, hi); }
; #define SEG(cnt, ...) if (r < (cnt)) { p0_transpose_item(__VA_ARGS__); continue; } r -= (cnt);
; __device__ __forceinline__ void p0_transpose_item(const float* W, int K, int N, bf16_t* WT, int row_off, LAS float* scr, int item, int lane,
;                                                   const float* gain, int sc_lo, int sc_hi, float sc) {
;     ...
; #pragma unroll
;     for (int i = 0; i < 8; ++i) {
;         const int kk = (lane >> 3) + 8 * i;
;         const float gm = gain ? gain[k0 + kk] : 1.0f;
;         LAS float* sp = scr + kk * 33 + 4 * (lane & 7);
;         sp[0] = wv[i][0] * gm; sp[1] = wv[i][1] * gm; sp[2] = wv[i][2] * gm; sp[3] = wv[i][3] * gm;
;     }
;     asm volatile("s_waitcnt lgkmcnt(0)" ::: "memory");
;     const int c = lane & 7;
; #pragma unroll
;     for (int j = 0; j < 4; ++j) {
;         const int n = (lane >> 3) + 8 * j; const LAS float* s = scr + (8 * c) * 33 + n;
;         const float mlt = (n0 + n >= sc_lo && n0 + n < sc_hi) ? sc : 1.0f;
;         u32x4 o; o.x = pk2(s[0 * 33] * mlt, s[1 * 33] * mlt); o.y = pk2(s[2 * 33] * mlt, s[3 * 33] * mlt);
;         o.z = pk2(s[4 * 33] * mlt, s[5 * 33] * mlt); o.w = pk2(s[6 * 33] * mlt, s[7 * 33] * mlt);
;         *(u32x4*)(WT + (size_t)(row_off + n0 + n) * K + k0 + 8 * c) = o;
;     }
; __global__ void __launch_bounds__(NTHREADS, 2) hybrid_fwd(Params P) {
;     ...
;             SEG(4096, w_out_ret + (size_t)4096 * 2048, 4096, 2048, WoutR + (size_t)2048 * 4096, 0, scr, r, lane, nullptr, 0, 0, 1.f)
.Lp0x_last_ie_B:
	s_waitcnt vmcnt(0)
	s_lshr_b32 s9, s42, 3
	s_mul_i32 s9, s9, 0xc31
	s_lshr_b32 s9, s9, 16
	s_mul_i32 s12, s9, 0xa8
	s_sub_i32 s12, s42, s12
	v_mul_f32_e32 v50, v50, v82
	v_mul_f32_e32 v51, v51, v82
	v_mul_f32_e32 v52, v52, v82
	v_mul_f32_e32 v53, v53, v82
	ds_write2_b32 v6, v50, v51 offset1:1
	ds_write2_b32 v6, v52, v53 offset0:2 offset1:3
	v_mul_f32_e32 v54, v54, v83
	v_mul_f32_e32 v55, v55, v83
	v_mul_f32_e32 v56, v56, v83
	v_mul_f32_e32 v57, v57, v83
	v_add_u32_e32 v0, 0x420, v6
	ds_write2_b32 v0, v54, v55 offset1:1
	ds_write2_b32 v0, v56, v57 offset0:2 offset1:3
	v_mul_f32_e32 v58, v58, v84
	v_mul_f32_e32 v59, v59, v84
	v_mul_f32_e32 v60, v60, v84
	v_mul_f32_e32 v61, v61, v84
	v_add_u32_e32 v0, 0x840, v6
	ds_write2_b32 v0, v58, v59 offset1:1
	ds_write2_b32 v0, v60, v61 offset0:2 offset1:3
	v_mul_f32_e32 v62, v62, v85
	v_mul_f32_e32 v63, v63, v85
	v_mul_f32_e32 v64, v64, v85
	v_mul_f32_e32 v65, v65, v85
	v_add_u32_e32 v0, 0xc60, v6
	ds_write2_b32 v0, v62, v63 offset1:1
	ds_write2_b32 v0, v64, v65 offset0:2 offset1:3
	v_mul_f32_e32 v66, v66, v86
	v_mul_f32_e32 v67, v67, v86
	v_mul_f32_e32 v68, v68, v86
	v_mul_f32_e32 v69, v69, v86
	v_add_u32_e32 v0, 0x1080, v6
	ds_write2_b32 v0, v66, v67 offset1:1
	ds_write2_b32 v0, v68, v69 offset0:2 offset1:3
	v_mul_f32_e32 v70, v70, v87
	v_mul_f32_e32 v71, v71, v87
	v_mul_f32_e32 v72, v72, v87
	v_mul_f32_e32 v73, v73, v87
	v_add_u32_e32 v0, 0x14a0, v6
	ds_write2_b32 v0, v70, v71 offset1:1
	ds_write2_b32 v0, v72, v73 offset0:2 offset1:3
	v_mul_f32_e32 v74, v74, v88
	v_mul_f32_e32 v75, v75, v88
	v_mul_f32_e32 v76, v76, v88
	v_mul_f32_e32 v77, v77, v88
	v_add_u32_e32 v0, 0x18c0, v6
	ds_write2_b32 v0, v74, v75 offset1:1
	ds_write2_b32 v0, v76, v77 offset0:2 offset1:3
	v_mul_f32_e32 v78, v78, v89
	v_mul_f32_e32 v79, v79, v89
	v_mul_f32_e32 v80, v80, v89
	v_mul_f32_e32 v81, v81, v89
	v_add_u32_e32 v0, 0x1ce0, v6
	ds_write2_b32 v0, v78, v79 offset1:1
	ds_write2_b32 v0, v80, v81 offset0:2 offset1:3
	s_waitcnt lgkmcnt(0)
	ds_read_b32 v90, v7 offset:0
	ds_read_b32 v91, v7 offset:132
	ds_read_b32 v92, v7 offset:264
	ds_read_b32 v93, v7 offset:396
	ds_read_b32 v94, v7 offset:528
	ds_read_b32 v95, v7 offset:660
	ds_read_b32 v96, v7 offset:792
	ds_read_b32 v97, v7 offset:924
	ds_read_b32 v98, v7 offset:32
	ds_read_b32 v99, v7 offset:164
	ds_read_b32 v100, v7 offset:296
	ds_read_b32 v101, v7 offset:428
	ds_read_b32 v102, v7 offset:560
	ds_read_b32 v103, v7 offset:692
	ds_read_b32 v104, v7 offset:824
	ds_read_b32 v105, v7 offset:956
	ds_read_b32 v106, v7 offset:64
	ds_read_b32 v107, v7 offset:196
	ds_read_b32 v108, v7 offset:328
	ds_read_b32 v109, v7 offset:460
	ds_read_b32 v110, v7 offset:592
	ds_read_b32 v111, v7 offset:724
	ds_read_b32 v112, v7 offset:856
	ds_read_b32 v113, v7 offset:988
	ds_read_b32 v114, v7 offset:96
	ds_read_b32 v115, v7 offset:228
	ds_read_b32 v116, v7 offset:360
	ds_read_b32 v117, v7 offset:492
	ds_read_b32 v118, v7 offset:624
	ds_read_b32 v119, v7 offset:756
	ds_read_b32 v120, v7 offset:888
	ds_read_b32 v121, v7 offset:1020
	s_waitcnt lgkmcnt(0)
	s_mul_i32 s34, s12, 0x20000
	s_lshl_b32 s35, s9, 7
	s_add_i32 s34, s34, s35
	s_add_u32 s40, s30, s34
	s_addc_u32 s41, s31, 0
	v_cvt_pk_bf16_f32 v122, v90, v91
	v_cvt_pk_bf16_f32 v123, v92, v93
	v_cvt_pk_bf16_f32 v124, v94, v95
	v_cvt_pk_bf16_f32 v125, v96, v97
	global_store_dwordx4 v8, v[122:125], s[40:41]
	s_add_u32 s40, s40, 0x8000
	s_addc_u32 s41, s41, 0
	v_cvt_pk_bf16_f32 v126, v98, v99
	v_cvt_pk_bf16_f32 v127, v100, v101
	v_cvt_pk_bf16_f32 v128, v102, v103
	v_cvt_pk_bf16_f32 v129, v104, v105
	global_store_dwordx4 v8, v[126:129], s[40:41]
	s_add_u32 s40, s40, 0x8000
	s_addc_u32 s41, s41, 0
	v_cvt_pk_bf16_f32 v130, v106, v107
	v_cvt_pk_bf16_f32 v131, v108, v109
	v_cvt_pk_bf16_f32 v132, v110, v111
	v_cvt_pk_bf16_f32 v133, v112, v113
	global_store_dwordx4 v8, v[130:133], s[40:41]
	s_add_u32 s40, s40, 0x8000
	s_addc_u32 s41, s41, 0
	v_cvt_pk_bf16_f32 v134, v114, v115
	v_cvt_pk_bf16_f32 v135, v116, v117
	v_cvt_pk_bf16_f32 v136, v118, v119
	v_cvt_pk_bf16_f32 v137, v120, v121
	global_store_dwordx4 v8, v[134:137], s[40:41]
.Lp0x_done_ie:
	s_load_dwordx2 s[26:27], s[96:97], 0x88
	v_readlane_b32 s30, v254, 42
	v_readlane_b32 s31, v254, 43
	v_mul_u32_u24_e32 v4, 0x2000, v2
	v_lshl_add_u32 v4, v3, 4, v4
	v_mul_u32_u24_e32 v8, 0x2000, v2
	v_lshl_add_u32 v8, v3, 4, v8
	s_mov_b32 s6, s43
	s_waitcnt lgkmcnt(0)
	s_add_u32 s26, s26, 0x2000000
	s_addc_u32 s27, s27, 0
	s_add_u32 s30, s30, 0xaa00000
	s_addc_u32 s31, s31, 0
	s_cmpk_ge_i32 s6, 0x1000
	s_cbranch_scc1 .Lp0x_done_or
	s_lshr_b32 s9, s6, 6
	s_and_b32 s12, s6, 63
	s_mul_i32 s13, s9, 0x80000
	s_lshl_b32 s34, s12, 7
	s_add_i32 s13, s13, s34
	s_add_u32 s36, s26, s13
	s_addc_u32 s37, s27, 0
	global_load_dwordx4 v[10:13], v4, s[36:37]
	s_add_u32 s36, s36, 0x10000
	s_addc_u32 s37, s37, 0
	global_load_dwordx4 v[14:17], v4, s[36:37]
	s_add_u32 s36, s36, 0x10000
	s_addc_u32 s37, s37, 0
	global_load_dwordx4 v[18:21], v4, s[36:37]
	s_add_u32 s36, s36, 0x10000
	s_addc_u32 s37, s37, 0
	global_load_dwordx4 v[22:25], v4, s[36:37]
	s_add_u32 s36, s36, 0x10000
	s_addc_u32 s37, s37, 0
	global_load_dwordx4 v[26:29], v4, s[36:37]
	s_add_u32 s36, s36, 0x10000
	s_addc_u32 s37, s37, 0
	global_load_dwordx4 v[30:33], v4, s[36:37]
	s_add_u32 s36, s36, 0x10000
	s_addc_u32 s37, s37, 0
	global_load_dwordx4 v[34:37], v4, s[36:37]
	s_add_u32 s36, s36, 0x10000
	s_addc_u32 s37, s37, 0
	global_load_dwordx4 v[38:41], v4, s[36:37]
; #define LAS __attribute__((address_space(3)))
; __device__ __forceinline__ unsigned pk2(float lo, float hi) { return pg8::cvt_pk_bf16(lo, hi); }
; __device__ __forceinline__ void p0_transpose_item(const float* W, int K, int N, bf16_t* WT, int row_off, LAS float* scr, int item, int lane,
;                                                   const float* gain, int sc_lo, int sc_hi, float sc) {
;     ...
;     for (int i = 0; i < 8; ++i) wv[i] = *(const f32x4*)(W + (size_t)(k0 + (lane >> 3) + 8 * i) * N + n0 + 4 * (lane & 7));
; #pragma unroll
;     for (int i = 0; i < 8; ++i) {
;         const int kk = (lane >> 3) + 8 * i;
;         const float gm = gain ? gain[k0 + kk] : 1.0f;
;         LAS float* sp = scr + kk * 33 + 4 * (lane & 7);
;         sp[0] = wv[i][0] * gm; sp[1] = wv[i][1] * gm; sp[2] = wv[i][2] * gm; sp[3] = wv[i][3] * gm;
;     }
;     asm volatile("s_waitcnt lgkmcnt(0)" ::: "memory");
;     const int c = lane & 7;
; #pragma unroll
;     for (int j = 0; j < 4; ++j) {
;         const int n = (lane >> 3) + 8 * j; const LAS float* s = scr + (8 * c) * 33 + n;
;         const float mlt = (n0 + n >= sc_lo && n0 + n < sc_hi) ? sc : 1.0f;
;         u32x4 o; o.x = pk2(s[0 * 33] * mlt, s[1 * 33] * mlt); o.y = pk2(s[2 * 33] * mlt, s[3 * 33] * mlt);
;         o.z = pk2(s[4 * 33] * mlt, s[5 * 33] * mlt); o.w = pk2(s[6 * 33] * mlt, s[7 * 33] * mlt);
;         *(u32x4*)(WT + (size_t)(row_off + n0 + n) * K + k0 + 8 * c) = o;
;     }
.Lp0x_loop_or:
	s_add_i32 s42, s6, s7
	s_cmpk_ge_i32 s42, 0x1000
	s_cbranch_scc1 .Lp0x_last_or_A
	s_lshr_b32 s9, s42, 6
	s_and_b32 s12, s42, 63
	s_mul_i32 s13, s9, 0x80000
	s_lshl_b32 s34, s12, 7
	s_add_i32 s13, s13, s34
	s_add_u32 s36, s26, s13
	s_addc_u32 s37, s27, 0
	global_load_dwordx4 v[50:53], v4, s[36:37]
	s_add_u32 s36, s36, 0x10000
	s_addc_u32 s37, s37, 0
	global_load_dwordx4 v[54:57], v4, s[36:37]
	s_add_u32 s36, s36, 0x10000
	s_addc_u32 s37, s37, 0
	global_load_dwordx4 v[58:61], v4, s[36:37]
	s_add_u32 s36, s36, 0x10000
	s_addc_u32 s37, s37, 0
	global_load_dwordx4 v[62:65], v4, s[36:37]
	s_add_u32 s36, s36, 0x10000
	s_addc_u32 s37, s37, 0
	global_load_dwordx4 v[66:69], v4, s[36:37]
	s_add_u32 s36, s36, 0x10000
	s_addc_u32 s37, s37, 0
	global_load_dwordx4 v[70:73], v4, s[36:37]
	s_add_u32 s36, s36, 0x10000
	s_addc_u32 s37, s37, 0
	global_load_dwordx4 v[74:77], v4, s[36:37]
	s_add_u32 s36, s36, 0x10000
	s_addc_u32 s37, s37, 0
	global_load_dwordx4 v[78:81], v4, s[36:37]
	s_waitcnt vmcnt(8)
	s_lshr_b32 s9, s6, 6
	s_and_b32 s12, s6, 63
	ds_write2_b32 v6, v10, v11 offset1:1
	ds_write2_b32 v6, v12, v13 offset0:2 offset1:3
	v_add_u32_e32 v0, 0x420, v6
	ds_write2_b32 v0, v14, v15 offset1:1
	ds_write2_b32 v0, v16, v17 offset0:2 offset1:3
	v_add_u32_e32 v0, 0x840, v6
	ds_write2_b32 v0, v18, v19 offset1:1
	ds_write2_b32 v0, v20, v21 offset0:2 offset1:3
	v_add_u32_e32 v0, 0xc60, v6
	ds_write2_b32 v0, v22, v23 offset1:1
	ds_write2_b32 v0, v24, v25 offset0:2 offset1:3
	v_add_u32_e32 v0, 0x1080, v6
	ds_write2_b32 v0, v26, v27 offset1:1
	ds_write2_b32 v0, v28, v29 offset0:2 offset1:3
	v_add_u32_e32 v0, 0x14a0, v6
	ds_write2_b32 v0, v30, v31 offset1:1
	ds_write2_b32 v0, v32, v33 offset0:2 offset1:3
	v_add_u32_e32 v0, 0x18c0, v6
	ds_write2_b32 v0, v34, v35 offset1:1
	ds_write2_b32 v0, v36, v37 offset0:2 offset1:3
	v_add_u32_e32 v0, 0x1ce0, v6
	ds_write2_b32 v0, v38, v39 offset1:1
	ds_write2_b32 v0, v40, v41 offset0:2 offset1:3
	s_waitcnt lgkmcnt(0)
	ds_read_b32 v90, v7 offset:0
	ds_read_b32 v91, v7 offset:132
	ds_read_b32 v92, v7 offset:264
	ds_read_b32 v93, v7 offset:396
	ds_read_b32 v94, v7 offset:528
	ds_read_b32 v95, v7 offset:660
	ds_read_b32 v96, v7 offset:792
	ds_read_b32 v97, v7 offset:924
	ds_read_b32 v98, v7 offset:32
	ds_read_b32 v99, v7 offset:164
	ds_read_b32 v100, v7 offset:296
	ds_read_b32 v101, v7 offset:428
	ds_read_b32 v102, v7 offset:560
	ds_read_b32 v103, v7 offset:692
	ds_read_b32 v104, v7 offset:824
	ds_read_b32 v105, v7 offset:956
	ds_read_b32 v106, v7 offset:64
	ds_read_b32 v107, v7 offset:196
	ds_read_b32 v108, v7 offset:328
	ds_read_b32 v109, v7 offset:460
	ds_read_b32 v110, v7 offset:592
	ds_read_b32 v111, v7 offset:724
	ds_read_b32 v112, v7 offset:856
	ds_read_b32 v113, v7 offset:988
	ds_read_b32 v114, v7 offset:96
	ds_read_b32 v115, v7 offset:228
	ds_read_b32 v116, v7 offset:360
	ds_read_b32 v117, v7 offset:492
	ds_read_b32 v118, v7 offset:624
	ds_read_b32 v119, v7 offset:756
	ds_read_b32 v120, v7 offset:888
	ds_read_b32 v121, v7 offset:1020
	s_waitcnt lgkmcnt(0)
	s_mul_i32 s34, s12, 0x40000
	s_lshl_b32 s35, s9, 7
	s_add_i32 s34, s34, s35
	s_add_u32 s40, s30, s34
	s_addc_u32 s41, s31, 0
	v_cvt_pk_bf16_f32 v122, v90, v91
	v_cvt_pk_bf16_f32 v123, v92, v93
	v_cvt_pk_bf16_f32 v124, v94, v95
	v_cvt_pk_bf16_f32 v125, v96, v97
	global_store_dwordx4 v8, v[122:125], s[40:41]
	s_add_u32 s40, s40, 0x10000
	s_addc_u32 s41, s41, 0
	v_cvt_pk_bf16_f32 v126, v98, v99
	v_cvt_pk_bf16_f32 v127, v100, v101
	v_cvt_pk_bf16_f32 v128, v102, v103
	v_cvt_pk_bf16_f32 v129, v104, v105
	global_store_dwordx4 v8, v[126:129], s[40:41]
	s_add_u32 s40, s40, 0x10000
	s_addc_u32 s41, s41, 0
	v_cvt_pk_bf16_f32 v130, v106, v107
	v_cvt_pk_bf16_f32 v131, v108, v109
	v_cvt_pk_bf16_f32 v132, v110, v111
	v_cvt_pk_bf16_f32 v133, v112, v113
	global_store_dwordx4 v8, v[130:133], s[40:41]
	s_add_u32 s40, s40, 0x10000
	s_addc_u32 s41, s41, 0
	v_cvt_pk_bf16_f32 v134, v114, v115
	v_cvt_pk_bf16_f32 v135, v116, v117
	v_cvt_pk_bf16_f32 v136, v118, v119
	v_cvt_pk_bf16_f32 v137, v120, v121
	global_store_dwordx4 v8, v[134:137], s[40:41]
	s_add_i32 s6, s42, s7
	s_cmpk_ge_i32 s6, 0x1000
	s_cbranch_scc1 .Lp0x_last_or_B
	s_lshr_b32 s9, s6, 6
	s_and_b32 s12, s6, 63
	s_mul_i32 s13, s9, 0x80000
	s_lshl_b32 s34, s12, 7
	s_add_i32 s13, s13, s34
	s_add_u32 s36, s26, s13
	s_addc_u32 s37, s27, 0
	global_load_dwordx4 v[10:13], v4, s[36:37]
	s_add_u32 s36, s36, 0x10000
	s_addc_u32 s37, s37, 0
	global_load_dwordx4 v[14:17], v4, s[36:37]
	s_add_u32 s36, s36, 0x10000
	s_addc_u32 s37, s37, 0
	global_load_dwordx4 v[18:21], v4, s[36:37]
	s_add_u32 s36, s36, 0x10000
	s_addc_u32 s37, s37, 0
	global_load_dwordx4 v[22:25], v4, s[36:37]
	s_add_u32 s36, s36, 0x10000
	s_addc_u32 s37, s37, 0
	global_load_dwordx4 v[26:29], v4, s[36:37]
	s_add_u32 s36, s36, 0x10000
	s_addc_u32 s37, s37, 0
	global_load_dwordx4 v[30:33], v4, s[36:37]
	s_add_u32 s36, s36, 0x10000
	s_addc_u32 s37, s37, 0
	global_load_dwordx4 v[34:37], v4, s[36:37]
	s_add_u32 s36, s36, 0x10000
	s_addc_u32 s37, s37, 0
	global_load_dwordx4 v[38:41], v4, s[36:37]
	s_waitcnt vmcnt(8)
	s_lshr_b32 s9, s42, 6
	s_and_b32 s12, s42, 63
	ds_write2_b32 v6, v50, v51 offset1:1
	ds_write2_b32 v6, v52, v53 offset0:2 offset1:3
	v_add_u32_e32 v0, 0x420, v6
	ds_write2_b32 v0, v54, v55 offset1:1
	ds_write2_b32 v0, v56, v57 offset0:2 offset1:3
	v_add_u32_e32 v0, 0x840, v6
	ds_write2_b32 v0, v58, v59 offset1:1
	ds_write2_b32 v0, v60, v61 offset0:2 offset1:3
	v_add_u32_e32 v0, 0xc60, v6
	ds_write2_b32 v0, v62, v63 offset1:1
	ds_write2_b32 v0, v64, v65 offset0:2 offset1:3
	v_add_u32_e32 v0, 0x1080, v6
	ds_write2_b32 v0, v66, v67 offset1:1
	ds_write2_b32 v0, v68, v69 offset0:2 offset1:3
	v_add_u32_e32 v0, 0x14a0, v6
	ds_write2_b32 v0, v70, v71 offset1:1
	ds_write2_b32 v0, v72, v73 offset0:2 offset1:3
	v_add_u32_e32 v0, 0x18c0, v6
	ds_write2_b32 v0, v74, v75 offset1:1
	ds_write2_b32 v0, v76, v77 offset0:2 offset1:3
	v_add_u32_e32 v0, 0x1ce0, v6
	ds_write2_b32 v0, v78, v79 offset1:1
	ds_write2_b32 v0, v80, v81 offset0:2 offset1:3
	s_waitcnt lgkmcnt(0)
; #define LAS __attribute__((address_space(3)))
; __device__ __forceinline__ unsigned pk2(float lo, float hi) { return pg8::cvt_pk_bf16(lo, hi); }
; __device__ __forceinline__ void p0_transpose_item(const float* W, int K, int N, bf16_t* WT, int row_off, LAS float* scr, int item, int lane,
;                                                   const float* gain, int sc_lo, int sc_hi, float sc) {
;     ...
;     for (int i = 0; i < 8; ++i) wv[i] = *(const f32x4*)(W + (size_t)(k0 + (lane >> 3) + 8 * i) * N + n0 + 4 * (lane & 7));
; #pragma unroll
;     for (int i = 0; i < 8; ++i) {
;         const int kk = (lane >> 3) + 8 * i;
;         const float gm = gain ? gain[k0 + kk] : 1.0f;
;         LAS float* sp = scr + kk * 33 + 4 * (lane & 7);
;         sp[0] = wv[i][0] * gm; sp[1] = wv[i][1] * gm; sp[2] = wv[i][2] * gm; sp[3] = wv[i][3] * gm;
;     }
;     asm volatile("s_waitcnt lgkmcnt(0)" ::: "memory");
;     const int c = lane & 7;
; #pragma unroll
;     for (int j = 0; j < 4; ++j) {
;         const int n = (lane >> 3) + 8 * j; const LAS float* s = scr + (8 * c) * 33 + n;
;         const float mlt = (n0 + n >= sc_lo && n0 + n < sc_hi) ? sc : 1.0f;
;         u32x4 o; o.x = pk2(s[0 * 33] * mlt, s[1 * 33] * mlt); o.y = pk2(s[2 * 33] * mlt, s[3 * 33] * mlt);
;         o.z = pk2(s[4 * 33] * mlt, s[5 * 33] * mlt); o.w = pk2(s[6 * 33] * mlt, s[7 * 33] * mlt);
;         *(u32x4*)(WT + (size_t)(row_off + n0 + n) * K + k0 + 8 * c) = o;
;     }
	ds_read_b32 v90, v7 offset:0
	ds_read_b32 v91, v7 offset:132
	ds_read_b32 v92, v7 offset:264
	ds_read_b32 v93, v7 offset:396
	ds_read_b32 v94, v7 offset:528
	ds_read_b32 v95, v7 offset:660
	ds_read_b32 v96, v7 offset:792
	ds_read_b32 v97, v7 offset:924
	ds_read_b32 v98, v7 offset:32
	ds_read_b32 v99, v7 offset:164
	ds_read_b32 v100, v7 offset:296
	ds_read_b32 v101, v7 offset:428
	ds_read_b32 v102, v7 offset:560
	ds_read_b32 v103, v7 offset:692
	ds_read_b32 v104, v7 offset:824
	ds_read_b32 v105, v7 offset:956
	ds_read_b32 v106, v7 offset:64
	ds_read_b32 v107, v7 offset:196
	ds_read_b32 v108, v7 offset:328
	ds_read_b32 v109, v7 offset:460
	ds_read_b32 v110, v7 offset:592
	ds_read_b32 v111, v7 offset:724
	ds_read_b32 v112, v7 offset:856
	ds_read_b32 v113, v7 offset:988
	ds_read_b32 v114, v7 offset:96
	ds_read_b32 v115, v7 offset:228
	ds_read_b32 v116, v7 offset:360
	ds_read_b32 v117, v7 offset:492
	ds_read_b32 v118, v7 offset:624
	ds_read_b32 v119, v7 offset:756
	ds_read_b32 v120, v7 offset:888
	ds_read_b32 v121, v7 offset:1020
	s_waitcnt lgkmcnt(0)
	s_mul_i32 s34, s12, 0x40000
	s_lshl_b32 s35, s9, 7
	s_add_i32 s34, s34, s35
	s_add_u32 s40, s30, s34
	s_addc_u32 s41, s31, 0
	v_cvt_pk_bf16_f32 v122, v90, v91
	v_cvt_pk_bf16_f32 v123, v92, v93
	v_cvt_pk_bf16_f32 v124, v94, v95
	v_cvt_pk_bf16_f32 v125, v96, v97
	global_store_dwordx4 v8, v[122:125], s[40:41]
	s_add_u32 s40, s40, 0x10000
	s_addc_u32 s41, s41, 0
	v_cvt_pk_bf16_f32 v126, v98, v99
	v_cvt_pk_bf16_f32 v127, v100, v101
	v_cvt_pk_bf16_f32 v128, v102, v103
	v_cvt_pk_bf16_f32 v129, v104, v105
	global_store_dwordx4 v8, v[126:129], s[40:41]
	s_add_u32 s40, s40, 0x10000
	s_addc_u32 s41, s41, 0
	v_cvt_pk_bf16_f32 v130, v106, v107
	v_cvt_pk_bf16_f32 v131, v108, v109
	v_cvt_pk_bf16_f32 v132, v110, v111
	v_cvt_pk_bf16_f32 v133, v112, v113
	global_store_dwordx4 v8, v[130:133], s[40:41]
	s_add_u32 s40, s40, 0x10000
	s_addc_u32 s41, s41, 0
	v_cvt_pk_bf16_f32 v134, v114, v115
	v_cvt_pk_bf16_f32 v135, v116, v117
	v_cvt_pk_bf16_f32 v136, v118, v119
	v_cvt_pk_bf16_f32 v137, v120, v121
	global_store_dwordx4 v8, v[134:137], s[40:41]
	s_branch .Lp0x_loop_or
.Lp0x_last_or_A:
	s_waitcnt vmcnt(0)
	s_lshr_b32 s9, s6, 6
	s_and_b32 s12, s6, 63
	ds_write2_b32 v6, v10, v11 offset1:1
	ds_write2_b32 v6, v12, v13 offset0:2 offset1:3
	v_add_u32_e32 v0, 0x420, v6
	ds_write2_b32 v0, v14, v15 offset1:1
	ds_write2_b32 v0, v16, v17 offset0:2 offset1:3
	v_add_u32_e32 v0, 0x840, v6
	ds_write2_b32 v0, v18, v19 offset1:1
	ds_write2_b32 v0, v20, v21 offset0:2 offset1:3
	v_add_u32_e32 v0, 0xc60, v6
	ds_write2_b32 v0, v22, v23 offset1:1
	ds_write2_b32 v0, v24, v25 offset0:2 offset1:3
	v_add_u32_e32 v0, 0x1080, v6
	ds_write2_b32 v0, v26, v27 offset1:1
	ds_write2_b32 v0, v28, v29 offset0:2 offset1:3
	v_add_u32_e32 v0, 0x14a0, v6
	ds_write2_b32 v0, v30, v31 offset1:1
	ds_write2_b32 v0, v32, v33 offset0:2 offset1:3
	v_add_u32_e32 v0, 0x18c0, v6
	ds_write2_b32 v0, v34, v35 offset1:1
	ds_write2_b32 v0, v36, v37 offset0:2 offset1:3
	v_add_u32_e32 v0, 0x1ce0, v6
	ds_write2_b32 v0, v38, v39 offset1:1
	ds_write2_b32 v0, v40, v41 offset0:2 offset1:3
	s_waitcnt lgkmcnt(0)
	ds_read_b32 v90, v7 offset:0
	ds_read_b32 v91, v7 offset:132
	ds_read_b32 v92, v7 offset:264
	ds_read_b32 v93, v7 offset:396
	ds_read_b32 v94, v7 offset:528
	ds_read_b32 v95, v7 offset:660
	ds_read_b32 v96, v7 offset:792
	ds_read_b32 v97, v7 offset:924
	ds_read_b32 v98, v7 offset:32
	ds_read_b32 v99, v7 offset:164
	ds_read_b32 v100, v7 offset:296
	ds_read_b32 v101, v7 offset:428
	ds_read_b32 v102, v7 offset:560
	ds_read_b32 v103, v7 offset:692
	ds_read_b32 v104, v7 offset:824
	ds_read_b32 v105, v7 offset:956
	ds_read_b32 v106, v7 offset:64
	ds_read_b32 v107, v7 offset:196
	ds_read_b32 v108, v7 offset:328
	ds_read_b32 v109, v7 offset:460
	ds_read_b32 v110, v7 offset:592
	ds_read_b32 v111, v7 offset:724
	ds_read_b32 v112, v7 offset:856
	ds_read_b32 v113, v7 offset:988
	ds_read_b32 v114, v7 offset:96
	ds_read_b32 v115, v7 offset:228
	ds_read_b32 v116, v7 offset:360
	ds_read_b32 v117, v7 offset:492
	ds_read_b32 v118, v7 offset:624
	ds_read_b32 v119, v7 offset:756
	ds_read_b32 v120, v7 offset:888
	ds_read_b32 v121, v7 offset:1020
	s_waitcnt lgkmcnt(0)
	s_mul_i32 s34, s12, 0x40000
	s_lshl_b32 s35, s9, 7
	s_add_i32 s34, s34, s35
	s_add_u32 s40, s30, s34
	s_addc_u32 s41, s31, 0
	v_cvt_pk_bf16_f32 v122, v90, v91
	v_cvt_pk_bf16_f32 v123, v92, v93
	v_cvt_pk_bf16_f32 v124, v94, v95
	v_cvt_pk_bf16_f32 v125, v96, v97
	global_store_dwordx4 v8, v[122:125], s[40:41]
	s_add_u32 s40, s40, 0x10000
	s_addc_u32 s41, s41, 0
	v_cvt_pk_bf16_f32 v126, v98, v99
	v_cvt_pk_bf16_f32 v127, v100, v101
	v_cvt_pk_bf16_f32 v128, v102, v103
	v_cvt_pk_bf16_f32 v129, v104, v105
	global_store_dwordx4 v8, v[126:129], s[40:41]
	s_add_u32 s40, s40, 0x10000
	s_addc_u32 s41, s41, 0
	v_cvt_pk_bf16_f32 v130, v106, v107
	v_cvt_pk_bf16_f32 v131, v108, v109
	v_cvt_pk_bf16_f32 v132, v110, v111
	v_cvt_pk_bf16_f32 v133, v112, v113
	global_store_dwordx4 v8, v[130:133], s[40:41]
	s_add_u32 s40, s40, 0x10000
	s_addc_u32 s41, s41, 0
	v_cvt_pk_bf16_f32 v134, v114, v115
	v_cvt_pk_bf16_f32 v135, v116, v117
	v_cvt_pk_bf16_f32 v136, v118, v119
	v_cvt_pk_bf16_f32 v137, v120, v121
	global_store_dwordx4 v8, v[134:137], s[40:41]
	s_branch .Lp0x_done_or
; #define LAS __attribute__((address_space(3)))
; __device__ __forceinline__ unsigned pk2(float lo, float hi) { return pg8::cvt_pk_bf16(lo, hi); }
; #define SEG(cnt, ...) if (r < (cnt)) { p0_transpose_item(__VA_ARGS__); continue; } r -= (cnt);
; __device__ __forceinline__ void p0_transpose_item(const float* W, int K, int N, bf16_t* WT, int row_off, LAS float* scr, int item, int lane,
;                                                   const float* gain, int sc_lo, int sc_hi, float sc) {
;     ...
; #pragma unroll
;     for (int i = 0; i < 8; ++i) {
;         const int kk = (lane >> 3) + 8 * i;
;         const float gm = gain ? gain[k0 + kk] : 1.0f;
;         LAS float* sp = scr + kk * 33 + 4 * (lane & 7);
;         sp[0] = wv[i][0] * gm; sp[1] = wv[i][1] * gm; sp[2] = wv[i][2] * gm; sp[3] = wv[i][3] * gm;
;     }
;     asm volatile("s_waitcnt lgkmcnt(0)" ::: "memory");
;     const int c = lane & 7;
; #pragma unroll
;     for (int j = 0; j < 4; ++j) {
;         const int n = (lane >> 3) + 8 * j; const LAS float* s = scr + (8 * c) * 33 + n;
;         const float mlt = (n0 + n >= sc_lo && n0 + n < sc_hi) ? sc : 1.0f;
;         u32x4 o; o.x = pk2(s[0 * 33] * mlt, s[1 * 33] * mlt); o.y = pk2(s[2 * 33] * mlt, s[3 * 33] * mlt);
;         o.z = pk2(s[4 * 33] * mlt, s[5 * 33] * mlt); o.w = pk2(s[6 * 33] * mlt, s[7 * 33] * mlt);
;         *(u32x4*)(WT + (size_t)(row_off + n0 + n) * K + k0 + 8 * c) = o;
;     }
; __global__ void __launch_bounds__(NTHREADS, 2) hybrid_fwd(Params P) {
;     ...
;             SEG(2048, w_out_even + (size_t)2048 * 2048, 2048, 2048, WoutE + (size_t)2048 * 2048, 0, scr, r, lane, nullptr, 0, 0, 1.f)
.Lp0x_last_or_B:
	s_waitcnt vmcnt(0)
	s_lshr_b32 s9, s42, 6
	s_and_b32 s12, s42, 63
	ds_write2_b32 v6, v50, v51 offset1:1
	ds_write2_b32 v6, v52, v53 offset0:2 offset1:3
	v_add_u32_e32 v0, 0x420, v6
	ds_write2_b32 v0, v54, v55 offset1:1
	ds_write2_b32 v0, v56, v57 offset0:2 offset1:3
	v_add_u32_e32 v0, 0x840, v6
	ds_write2_b32 v0, v58, v59 offset1:1
	ds_write2_b32 v0, v60, v61 offset0:2 offset1:3
	v_add_u32_e32 v0, 0xc60, v6
	ds_write2_b32 v0, v62, v63 offset1:1
	ds_write2_b32 v0, v64, v65 offset0:2 offset1:3
	v_add_u32_e32 v0, 0x1080, v6
	ds_write2_b32 v0, v66, v67 offset1:1
	ds_write2_b32 v0, v68, v69 offset0:2 offset1:3
	v_add_u32_e32 v0, 0x14a0, v6
	ds_write2_b32 v0, v70, v71 offset1:1
	ds_write2_b32 v0, v72, v73 offset0:2 offset1:3
	v_add_u32_e32 v0, 0x18c0, v6
	ds_write2_b32 v0, v74, v75 offset1:1
	ds_write2_b32 v0, v76, v77 offset0:2 offset1:3
	v_add_u32_e32 v0, 0x1ce0, v6
	ds_write2_b32 v0, v78, v79 offset1:1
	ds_write2_b32 v0, v80, v81 offset0:2 offset1:3
	s_waitcnt lgkmcnt(0)
	ds_read_b32 v90, v7 offset:0
	ds_read_b32 v91, v7 offset:132
	ds_read_b32 v92, v7 offset:264
	ds_read_b32 v93, v7 offset:396
	ds_read_b32 v94, v7 offset:528
	ds_read_b32 v95, v7 offset:660
	ds_read_b32 v96, v7 offset:792
	ds_read_b32 v97, v7 offset:924
	ds_read_b32 v98, v7 offset:32
	ds_read_b32 v99, v7 offset:164
	ds_read_b32 v100, v7 offset:296
	ds_read_b32 v101, v7 offset:428
	ds_read_b32 v102, v7 offset:560
	ds_read_b32 v103, v7 offset:692
	ds_read_b32 v104, v7 offset:824
	ds_read_b32 v105, v7 offset:956
	ds_read_b32 v106, v7 offset:64
	ds_read_b32 v107, v7 offset:196
	ds_read_b32 v108, v7 offset:328
	ds_read_b32 v109, v7 offset:460
	ds_read_b32 v110, v7 offset:592
	ds_read_b32 v111, v7 offset:724
	ds_read_b32 v112, v7 offset:856
	ds_read_b32 v113, v7 offset:988
	ds_read_b32 v114, v7 offset:96
	ds_read_b32 v115, v7 offset:228
	ds_read_b32 v116, v7 offset:360
	ds_read_b32 v117, v7 offset:492
	ds_read_b32 v118, v7 offset:624
	ds_read_b32 v119, v7 offset:756
	ds_read_b32 v120, v7 offset:888
	ds_read_b32 v121, v7 offset:1020
	s_waitcnt lgkmcnt(0)
	s_mul_i32 s34, s12, 0x40000
	s_lshl_b32 s35, s9, 7
	s_add_i32 s34, s34, s35
	s_add_u32 s40, s30, s34
	s_addc_u32 s41, s31, 0
	v_cvt_pk_bf16_f32 v122, v90, v91
	v_cvt_pk_bf16_f32 v123, v92, v93
	v_cvt_pk_bf16_f32 v124, v94, v95
	v_cvt_pk_bf16_f32 v125, v96, v97
	global_store_dwordx4 v8, v[122:125], s[40:41]
	s_add_u32 s40, s40, 0x10000
	s_addc_u32 s41, s41, 0
	v_cvt_pk_bf16_f32 v126, v98, v99
	v_cvt_pk_bf16_f32 v127, v100, v101
	v_cvt_pk_bf16_f32 v128, v102, v103
	v_cvt_pk_bf16_f32 v129, v104, v105
	global_store_dwordx4 v8, v[126:129], s[40:41]
	s_add_u32 s40, s40, 0x10000
	s_addc_u32 s41, s41, 0
	v_cvt_pk_bf16_f32 v130, v106, v107
	v_cvt_pk_bf16_f32 v131, v108, v109
	v_cvt_pk_bf16_f32 v132, v110, v111
	v_cvt_pk_bf16_f32 v133, v112, v113
	global_store_dwordx4 v8, v[130:133], s[40:41]
	s_add_u32 s40, s40, 0x10000
	s_addc_u32 s41, s41, 0
	v_cvt_pk_bf16_f32 v134, v114, v115
	v_cvt_pk_bf16_f32 v135, v116, v117
	v_cvt_pk_bf16_f32 v136, v118, v119
	v_cvt_pk_bf16_f32 v137, v120, v121
	global_store_dwordx4 v8, v[134:137], s[40:41]
.Lp0x_done_or:
	s_load_dwordx2 s[26:27], s[96:97], 0x78
	v_readlane_b32 s30, v254, 42
	v_readlane_b32 s31, v254, 43
	v_mul_u32_u24_e32 v4, 0x2000, v2
	v_lshl_add_u32 v4, v3, 4, v4
	v_mul_u32_u24_e32 v8, 0x1000, v2
	v_lshl_add_u32 v8, v3, 4, v8
	s_mov_b32 s6, s43
	s_waitcnt lgkmcnt(0)
	s_add_u32 s26, s26, 0x1000000
	s_addc_u32 s27, s27, 0
	s_add_u32 s30, s30, 0x3200000
	s_addc_u32 s31, s31, 0
	s_cmpk_ge_i32 s6, 0x800
	s_cbranch_scc1 .Lp0x_done_oe
	s_lshr_b32 s9, s6, 6
	s_and_b32 s12, s6, 63
	s_mul_i32 s13, s9, 0x80000
	s_lshl_b32 s34, s12, 7
	s_add_i32 s13, s13, s34
	s_add_u32 s36, s26, s13
	s_addc_u32 s37, s27, 0
	global_load_dwordx4 v[10:13], v4, s[36:37]
	s_add_u32 s36, s36, 0x10000
	s_addc_u32 s37, s37, 0
	global_load_dwordx4 v[14:17], v4, s[36:37]
	s_add_u32 s36, s36, 0x10000
	s_addc_u32 s37, s37, 0
	global_load_dwordx4 v[18:21], v4, s[36:37]
	s_add_u32 s36, s36, 0x10000
	s_addc_u32 s37, s37, 0
	global_load_dwordx4 v[22:25], v4, s[36:37]
	s_add_u32 s36, s36, 0x10000
	s_addc_u32 s37, s37, 0
	global_load_dwordx4 v[26:29], v4, s[36:37]
	s_add_u32 s36, s36, 0x10000
	s_addc_u32 s37, s37, 0
	global_load_dwordx4 v[30:33], v4, s[36:37]
	s_add_u32 s36, s36, 0x10000
	s_addc_u32 s37, s37, 0
	global_load_dwordx4 v[34:37], v4, s[36:37]
	s_add_u32 s36, s36, 0x10000
	s_addc_u32 s37, s37, 0
	global_load_dwordx4 v[38:41], v4, s[36:37]
; #define LAS __attribute__((address_space(3)))
; __device__ __forceinline__ unsigned pk2(float lo, float hi) { return pg8::cvt_pk_bf16(lo, hi); }
; __device__ __forceinline__ void p0_transpose_item(const float* W, int K, int N, bf16_t* WT, int row_off, LAS float* scr, int item, int lane,
;                                                   const float* gain, int sc_lo, int sc_hi, float sc) {
;     ...
;     for (int i = 0; i < 8; ++i) wv[i] = *(const f32x4*)(W + (size_t)(k0 + (lane >> 3) + 8 * i) * N + n0 + 4 * (lane & 7));
; #pragma unroll
;     for (int i = 0; i < 8; ++i) {
;         const int kk = (lane >> 3) + 8 * i;
;         const float gm = gain ? gain[k0 + kk] : 1.0f;
;         LAS float* sp = scr + kk * 33 + 4 * (lane & 7);
;         sp[0] = wv[i][0] * gm; sp[1] = wv[i][1] * gm; sp[2] = wv[i][2] * gm; sp[3] = wv[i][3] * gm;
;     }
;     asm volatile("s_waitcnt lgkmcnt(0)" ::: "memory");
;     const int c = lane & 7;
; #pragma unroll
;     for (int j = 0; j < 4; ++j) {
;         const int n = (lane >> 3) + 8 * j; const LAS float* s = scr + (8 * c) * 33 + n;
;         const float mlt = (n0 + n >= sc_lo && n0 + n < sc_hi) ? sc : 1.0f;
;         u32x4 o; o.x = pk2(s[0 * 33] * mlt, s[1 * 33] * mlt); o.y = pk2(s[2 * 33] * mlt, s[3 * 33] * mlt);
;         o.z = pk2(s[4 * 33] * mlt, s[5 * 33] * mlt); o.w = pk2(s[6 * 33] * mlt, s[7 * 33] * mlt);
;         *(u32x4*)(WT + (size_t)(row_off + n0 + n) * K + k0 + 8 * c) = o;
;     }
.Lp0x_loop_oe:
	s_add_i32 s42, s6, s7
	s_cmpk_ge_i32 s42, 0x800
	s_cbranch_scc1 .Lp0x_last_oe_A
	s_lshr_b32 s9, s42, 6
	s_and_b32 s12, s42, 63
	s_mul_i32 s13, s9, 0x80000
	s_lshl_b32 s34, s12, 7
	s_add_i32 s13, s13, s34
	s_add_u32 s36, s26, s13
	s_addc_u32 s37, s27, 0
	global_load_dwordx4 v[50:53], v4, s[36:37]
	s_add_u32 s36, s36, 0x10000
	s_addc_u32 s37, s37, 0
	global_load_dwordx4 v[54:57], v4, s[36:37]
	s_add_u32 s36, s36, 0x10000
	s_addc_u32 s37, s37, 0
	global_load_dwordx4 v[58:61], v4, s[36:37]
	s_add_u32 s36, s36, 0x10000
	s_addc_u32 s37, s37, 0
	global_load_dwordx4 v[62:65], v4, s[36:37]
	s_add_u32 s36, s36, 0x10000
	s_addc_u32 s37, s37, 0
	global_load_dwordx4 v[66:69], v4, s[36:37]
	s_add_u32 s36, s36, 0x10000
	s_addc_u32 s37, s37, 0
	global_load_dwordx4 v[70:73], v4, s[36:37]
	s_add_u32 s36, s36, 0x10000
	s_addc_u32 s37, s37, 0
	global_load_dwordx4 v[74:77], v4, s[36:37]
	s_add_u32 s36, s36, 0x10000
	s_addc_u32 s37, s37, 0
	global_load_dwordx4 v[78:81], v4, s[36:37]
	s_waitcnt vmcnt(8)
	s_lshr_b32 s9, s6, 6
	s_and_b32 s12, s6, 63
	ds_write2_b32 v6, v10, v11 offset1:1
	ds_write2_b32 v6, v12, v13 offset0:2 offset1:3
	v_add_u32_e32 v0, 0x420, v6
	ds_write2_b32 v0, v14, v15 offset1:1
	ds_write2_b32 v0, v16, v17 offset0:2 offset1:3
	v_add_u32_e32 v0, 0x840, v6
	ds_write2_b32 v0, v18, v19 offset1:1
	ds_write2_b32 v0, v20, v21 offset0:2 offset1:3
	v_add_u32_e32 v0, 0xc60, v6
	ds_write2_b32 v0, v22, v23 offset1:1
	ds_write2_b32 v0, v24, v25 offset0:2 offset1:3
	v_add_u32_e32 v0, 0x1080, v6
	ds_write2_b32 v0, v26, v27 offset1:1
	ds_write2_b32 v0, v28, v29 offset0:2 offset1:3
	v_add_u32_e32 v0, 0x14a0, v6
	ds_write2_b32 v0, v30, v31 offset1:1
	ds_write2_b32 v0, v32, v33 offset0:2 offset1:3
	v_add_u32_e32 v0, 0x18c0, v6
	ds_write2_b32 v0, v34, v35 offset1:1
	ds_write2_b32 v0, v36, v37 offset0:2 offset1:3
	v_add_u32_e32 v0, 0x1ce0, v6
	ds_write2_b32 v0, v38, v39 offset1:1
	ds_write2_b32 v0, v40, v41 offset0:2 offset1:3
	s_waitcnt lgkmcnt(0)
	ds_read_b32 v90, v7 offset:0
	ds_read_b32 v91, v7 offset:132
	ds_read_b32 v92, v7 offset:264
	ds_read_b32 v93, v7 offset:396
	ds_read_b32 v94, v7 offset:528
	ds_read_b32 v95, v7 offset:660
	ds_read_b32 v96, v7 offset:792
	ds_read_b32 v97, v7 offset:924
	ds_read_b32 v98, v7 offset:32
	ds_read_b32 v99, v7 offset:164
	ds_read_b32 v100, v7 offset:296
	ds_read_b32 v101, v7 offset:428
	ds_read_b32 v102, v7 offset:560
	ds_read_b32 v103, v7 offset:692
	ds_read_b32 v104, v7 offset:824
	ds_read_b32 v105, v7 offset:956
	ds_read_b32 v106, v7 offset:64
	ds_read_b32 v107, v7 offset:196
	ds_read_b32 v108, v7 offset:328
	ds_read_b32 v109, v7 offset:460
	ds_read_b32 v110, v7 offset:592
	ds_read_b32 v111, v7 offset:724
	ds_read_b32 v112, v7 offset:856
	ds_read_b32 v113, v7 offset:988
	ds_read_b32 v114, v7 offset:96
	ds_read_b32 v115, v7 offset:228
	ds_read_b32 v116, v7 offset:360
	ds_read_b32 v117, v7 offset:492
	ds_read_b32 v118, v7 offset:624
	ds_read_b32 v119, v7 offset:756
	ds_read_b32 v120, v7 offset:888
	ds_read_b32 v121, v7 offset:1020
	s_waitcnt lgkmcnt(0)
	s_mul_i32 s34, s12, 0x20000
	s_lshl_b32 s35, s9, 7
	s_add_i32 s34, s34, s35
	s_add_u32 s40, s30, s34
	s_addc_u32 s41, s31, 0
	v_cvt_pk_bf16_f32 v122, v90, v91
	v_cvt_pk_bf16_f32 v123, v92, v93
	v_cvt_pk_bf16_f32 v124, v94, v95
	v_cvt_pk_bf16_f32 v125, v96, v97
	global_store_dwordx4 v8, v[122:125], s[40:41]
	s_add_u32 s40, s40, 0x8000
	s_addc_u32 s41, s41, 0
	v_cvt_pk_bf16_f32 v126, v98, v99
	v_cvt_pk_bf16_f32 v127, v100, v101
	v_cvt_pk_bf16_f32 v128, v102, v103
	v_cvt_pk_bf16_f32 v129, v104, v105
	global_store_dwordx4 v8, v[126:129], s[40:41]
	s_add_u32 s40, s40, 0x8000
	s_addc_u32 s41, s41, 0
	v_cvt_pk_bf16_f32 v130, v106, v107
	v_cvt_pk_bf16_f32 v131, v108, v109
	v_cvt_pk_bf16_f32 v132, v110, v111
	v_cvt_pk_bf16_f32 v133, v112, v113
	global_store_dwordx4 v8, v[130:133], s[40:41]
	s_add_u32 s40, s40, 0x8000
	s_addc_u32 s41, s41, 0
	v_cvt_pk_bf16_f32 v134, v114, v115
	v_cvt_pk_bf16_f32 v135, v116, v117
	v_cvt_pk_bf16_f32 v136, v118, v119
	v_cvt_pk_bf16_f32 v137, v120, v121
	global_store_dwordx4 v8, v[134:137], s[40:41]
	s_add_i32 s6, s42, s7
	s_cmpk_ge_i32 s6, 0x800
	s_cbranch_scc1 .Lp0x_last_oe_B
	s_lshr_b32 s9, s6, 6
	s_and_b32 s12, s6, 63
	s_mul_i32 s13, s9, 0x80000
	s_lshl_b32 s34, s12, 7
	s_add_i32 s13, s13, s34
	s_add_u32 s36, s26, s13
	s_addc_u32 s37, s27, 0
	global_load_dwordx4 v[10:13], v4, s[36:37]
	s_add_u32 s36, s36, 0x10000
	s_addc_u32 s37, s37, 0
	global_load_dwordx4 v[14:17], v4, s[36:37]
	s_add_u32 s36, s36, 0x10000
	s_addc_u32 s37, s37, 0
	global_load_dwordx4 v[18:21], v4, s[36:37]
	s_add_u32 s36, s36, 0x10000
	s_addc_u32 s37, s37, 0
	global_load_dwordx4 v[22:25], v4, s[36:37]
	s_add_u32 s36, s36, 0x10000
	s_addc_u32 s37, s37, 0
	global_load_dwordx4 v[26:29], v4, s[36:37]
	s_add_u32 s36, s36, 0x10000
	s_addc_u32 s37, s37, 0
	global_load_dwordx4 v[30:33], v4, s[36:37]
	s_add_u32 s36, s36, 0x10000
	s_addc_u32 s37, s37, 0
	global_load_dwordx4 v[34:37], v4, s[36:37]
	s_add_u32 s36, s36, 0x10000
	s_addc_u32 s37, s37, 0
	global_load_dwordx4 v[38:41], v4, s[36:37]
	s_waitcnt vmcnt(8)
	s_lshr_b32 s9, s42, 6
	s_and_b32 s12, s42, 63
	ds_write2_b32 v6, v50, v51 offset1:1
	ds_write2_b32 v6, v52, v53 offset0:2 offset1:3
	v_add_u32_e32 v0, 0x420, v6
	ds_write2_b32 v0, v54, v55 offset1:1
	ds_write2_b32 v0, v56, v57 offset0:2 offset1:3
	v_add_u32_e32 v0, 0x840, v6
	ds_write2_b32 v0, v58, v59 offset1:1
	ds_write2_b32 v0, v60, v61 offset0:2 offset1:3
	v_add_u32_e32 v0, 0xc60, v6
	ds_write2_b32 v0, v62, v63 offset1:1
	ds_write2_b32 v0, v64, v65 offset0:2 offset1:3
	v_add_u32_e32 v0, 0x1080, v6
	ds_write2_b32 v0, v66, v67 offset1:1
	ds_write2_b32 v0, v68, v69 offset0:2 offset1:3
	v_add_u32_e32 v0, 0x14a0, v6
	ds_write2_b32 v0, v70, v71 offset1:1
	ds_write2_b32 v0, v72, v73 offset0:2 offset1:3
	v_add_u32_e32 v0, 0x18c0, v6
	ds_write2_b32 v0, v74, v75 offset1:1
	ds_write2_b32 v0, v76, v77 offset0:2 offset1:3
	v_add_u32_e32 v0, 0x1ce0, v6
	ds_write2_b32 v0, v78, v79 offset1:1
	ds_write2_b32 v0, v80, v81 offset0:2 offset1:3
	s_waitcnt lgkmcnt(0)
; #define LAS __attribute__((address_space(3)))
; __device__ __forceinline__ unsigned pk2(float lo, float hi) { return pg8::cvt_pk_bf16(lo, hi); }
; __device__ __forceinline__ void p0_transpose_item(const float* W, int K, int N, bf16_t* WT, int row_off, LAS float* scr, int item, int lane,
;                                                   const float* gain, int sc_lo, int sc_hi, float sc) {
;     ...
;     for (int i = 0; i < 8; ++i) wv[i] = *(const f32x4*)(W + (size_t)(k0 + (lane >> 3) + 8 * i) * N + n0 + 4 * (lane & 7));
; #pragma unroll
;     for (int i = 0; i < 8; ++i) {
;         const int kk = (lane >> 3) + 8 * i;
;         const float gm = gain ? gain[k0 + kk] : 1.0f;
;         LAS float* sp = scr + kk * 33 + 4 * (lane & 7);
;         sp[0] = wv[i][0] * gm; sp[1] = wv[i][1] * gm; sp[2] = wv[i][2] * gm; sp[3] = wv[i][3] * gm;
;     }
;     asm volatile("s_waitcnt lgkmcnt(0)" ::: "memory");
;     const int c = lane & 7;
; #pragma unroll
;     for (int j = 0; j < 4; ++j) {
;         const int n = (lane >> 3) + 8 * j; const LAS float* s = scr + (8 * c) * 33 + n;
;         const float mlt = (n0 + n >= sc_lo && n0 + n < sc_hi) ? sc : 1.0f;
;         u32x4 o; o.x = pk2(s[0 * 33] * mlt, s[1 * 33] * mlt); o.y = pk2(s[2 * 33] * mlt, s[3 * 33] * mlt);
;         o.z = pk2(s[4 * 33] * mlt, s[5 * 33] * mlt); o.w = pk2(s[6 * 33] * mlt, s[7 * 33] * mlt);
;         *(u32x4*)(WT + (size_t)(row_off + n0 + n) * K + k0 + 8 * c) = o;
;     }
	ds_read_b32 v90, v7 offset:0
	ds_read_b32 v91, v7 offset:132
	ds_read_b32 v92, v7 offset:264
	ds_read_b32 v93, v7 offset:396
	ds_read_b32 v94, v7 offset:528
	ds_read_b32 v95, v7 offset:660
	ds_read_b32 v96, v7 offset:792
	ds_read_b32 v97, v7 offset:924
	ds_read_b32 v98, v7 offset:32
	ds_read_b32 v99, v7 offset:164
	ds_read_b32 v100, v7 offset:296
	ds_read_b32 v101, v7 offset:428
	ds_read_b32 v102, v7 offset:560
	ds_read_b32 v103, v7 offset:692
	ds_read_b32 v104, v7 offset:824
	ds_read_b32 v105, v7 offset:956
	ds_read_b32 v106, v7 offset:64
	ds_read_b32 v107, v7 offset:196
	ds_read_b32 v108, v7 offset:328
	ds_read_b32 v109, v7 offset:460
	ds_read_b32 v110, v7 offset:592
	ds_read_b32 v111, v7 offset:724
	ds_read_b32 v112, v7 offset:856
	ds_read_b32 v113, v7 offset:988
	ds_read_b32 v114, v7 offset:96
	ds_read_b32 v115, v7 offset:228
	ds_read_b32 v116, v7 offset:360
	ds_read_b32 v117, v7 offset:492
	ds_read_b32 v118, v7 offset:624
	ds_read_b32 v119, v7 offset:756
	ds_read_b32 v120, v7 offset:888
	ds_read_b32 v121, v7 offset:1020
	s_waitcnt lgkmcnt(0)
	s_mul_i32 s34, s12, 0x20000
	s_lshl_b32 s35, s9, 7
	s_add_i32 s34, s34, s35
	s_add_u32 s40, s30, s34
	s_addc_u32 s41, s31, 0
	v_cvt_pk_bf16_f32 v122, v90, v91
	v_cvt_pk_bf16_f32 v123, v92, v93
	v_cvt_pk_bf16_f32 v124, v94, v95
	v_cvt_pk_bf16_f32 v125, v96, v97
	global_store_dwordx4 v8, v[122:125], s[40:41]
	s_add_u32 s40, s40, 0x8000
	s_addc_u32 s41, s41, 0
	v_cvt_pk_bf16_f32 v126, v98, v99
	v_cvt_pk_bf16_f32 v127, v100, v101
	v_cvt_pk_bf16_f32 v128, v102, v103
	v_cvt_pk_bf16_f32 v129, v104, v105
	global_store_dwordx4 v8, v[126:129], s[40:41]
	s_add_u32 s40, s40, 0x8000
	s_addc_u32 s41, s41, 0
	v_cvt_pk_bf16_f32 v130, v106, v107
	v_cvt_pk_bf16_f32 v131, v108, v109
	v_cvt_pk_bf16_f32 v132, v110, v111
	v_cvt_pk_bf16_f32 v133, v112, v113
	global_store_dwordx4 v8, v[130:133], s[40:41]
	s_add_u32 s40, s40, 0x8000
	s_addc_u32 s41, s41, 0
	v_cvt_pk_bf16_f32 v134, v114, v115
	v_cvt_pk_bf16_f32 v135, v116, v117
	v_cvt_pk_bf16_f32 v136, v118, v119
	v_cvt_pk_bf16_f32 v137, v120, v121
	global_store_dwordx4 v8, v[134:137], s[40:41]
	s_branch .Lp0x_loop_oe
.Lp0x_last_oe_A:
	s_waitcnt vmcnt(0)
	s_lshr_b32 s9, s6, 6
	s_and_b32 s12, s6, 63
	ds_write2_b32 v6, v10, v11 offset1:1
	ds_write2_b32 v6, v12, v13 offset0:2 offset1:3
	v_add_u32_e32 v0, 0x420, v6
	ds_write2_b32 v0, v14, v15 offset1:1
	ds_write2_b32 v0, v16, v17 offset0:2 offset1:3
	v_add_u32_e32 v0, 0x840, v6
	ds_write2_b32 v0, v18, v19 offset1:1
	ds_write2_b32 v0, v20, v21 offset0:2 offset1:3
	v_add_u32_e32 v0, 0xc60, v6
	ds_write2_b32 v0, v22, v23 offset1:1
	ds_write2_b32 v0, v24, v25 offset0:2 offset1:3
	v_add_u32_e32 v0, 0x1080, v6
	ds_write2_b32 v0, v26, v27 offset1:1
	ds_write2_b32 v0, v28, v29 offset0:2 offset1:3
	v_add_u32_e32 v0, 0x14a0, v6
	ds_write2_b32 v0, v30, v31 offset1:1
	ds_write2_b32 v0, v32, v33 offset0:2 offset1:3
	v_add_u32_e32 v0, 0x18c0, v6
	ds_write2_b32 v0, v34, v35 offset1:1
	ds_write2_b32 v0, v36, v37 offset0:2 offset1:3
	v_add_u32_e32 v0, 0x1ce0, v6
	ds_write2_b32 v0, v38, v39 offset1:1
	ds_write2_b32 v0, v40, v41 offset0:2 offset1:3
	s_waitcnt lgkmcnt(0)
	ds_read_b32 v90, v7 offset:0
	ds_read_b32 v91, v7 offset:132
	ds_read_b32 v92, v7 offset:264
	ds_read_b32 v93, v7 offset:396
	ds_read_b32 v94, v7 offset:528
	ds_read_b32 v95, v7 offset:660
	ds_read_b32 v96, v7 offset:792
	ds_read_b32 v97, v7 offset:924
	ds_read_b32 v98, v7 offset:32
	ds_read_b32 v99, v7 offset:164
	ds_read_b32 v100, v7 offset:296
	ds_read_b32 v101, v7 offset:428
	ds_read_b32 v102, v7 offset:560
	ds_read_b32 v103, v7 offset:692
	ds_read_b32 v104, v7 offset:824
	ds_read_b32 v105, v7 offset:956
	ds_read_b32 v106, v7 offset:64
	ds_read_b32 v107, v7 offset:196
	ds_read_b32 v108, v7 offset:328
	ds_read_b32 v109, v7 offset:460
	ds_read_b32 v110, v7 offset:592
	ds_read_b32 v111, v7 offset:724
	ds_read_b32 v112, v7 offset:856
	ds_read_b32 v113, v7 offset:988
	ds_read_b32 v114, v7 offset:96
	ds_read_b32 v115, v7 offset:228
	ds_read_b32 v116, v7 offset:360
	ds_read_b32 v117, v7 offset:492
	ds_read_b32 v118, v7 offset:624
	ds_read_b32 v119, v7 offset:756
	ds_read_b32 v120, v7 offset:888
	ds_read_b32 v121, v7 offset:1020
	s_waitcnt lgkmcnt(0)
	s_mul_i32 s34, s12, 0x20000
	s_lshl_b32 s35, s9, 7
	s_add_i32 s34, s34, s35
	s_add_u32 s40, s30, s34
	s_addc_u32 s41, s31, 0
	v_cvt_pk_bf16_f32 v122, v90, v91
	v_cvt_pk_bf16_f32 v123, v92, v93
	v_cvt_pk_bf16_f32 v124, v94, v95
	v_cvt_pk_bf16_f32 v125, v96, v97
	global_store_dwordx4 v8, v[122:125], s[40:41]
	s_add_u32 s40, s40, 0x8000
	s_addc_u32 s41, s41, 0
	v_cvt_pk_bf16_f32 v126, v98, v99
	v_cvt_pk_bf16_f32 v127, v100, v101
	v_cvt_pk_bf16_f32 v128, v102, v103
	v_cvt_pk_bf16_f32 v129, v104, v105
	global_store_dwordx4 v8, v[126:129], s[40:41]
	s_add_u32 s40, s40, 0x8000
	s_addc_u32 s41, s41, 0
	v_cvt_pk_bf16_f32 v130, v106, v107
	v_cvt_pk_bf16_f32 v131, v108, v109
	v_cvt_pk_bf16_f32 v132, v110, v111
	v_cvt_pk_bf16_f32 v133, v112, v113
	global_store_dwordx4 v8, v[130:133], s[40:41]
	s_add_u32 s40, s40, 0x8000
	s_addc_u32 s41, s41, 0
	v_cvt_pk_bf16_f32 v134, v114, v115
	v_cvt_pk_bf16_f32 v135, v116, v117
	v_cvt_pk_bf16_f32 v136, v118, v119
	v_cvt_pk_bf16_f32 v137, v120, v121
	global_store_dwordx4 v8, v[134:137], s[40:41]
	s_branch .Lp0x_done_oe
; #define LAS __attribute__((address_space(3)))
; __device__ __forceinline__ unsigned pk2(float lo, float hi) { return pg8::cvt_pk_bf16(lo, hi); }
; __device__ __forceinline__ unsigned xb_add(unsigned* p, unsigned v) { return __hip_atomic_fetch_add(p, v, __ATOMIC_RELAXED, __HIP_MEMORY_SCOPE_AGENT); }
; __device__ __forceinline__ void p0_transpose_item(const float* W, int K, int N, bf16_t* WT, int row_off, LAS float* scr, int item, int lane,
;                                                   const float* gain, int sc_lo, int sc_hi, float sc) {
;     ...
;     const int c = lane & 7;
; #pragma unroll
;     for (int j = 0; j < 4; ++j) {
;         const int n = (lane >> 3) + 8 * j; const LAS float* s = scr + (8 * c) * 33 + n;
;         const float mlt = (n0 + n >= sc_lo && n0 + n < sc_hi) ? sc : 1.0f;
;         u32x4 o; o.x = pk2(s[0 * 33] * mlt, s[1 * 33] * mlt); o.y = pk2(s[2 * 33] * mlt, s[3 * 33] * mlt);
;         o.z = pk2(s[4 * 33] * mlt, s[5 * 33] * mlt); o.w = pk2(s[6 * 33] * mlt, s[7 * 33] * mlt);
;         *(u32x4*)(WT + (size_t)(row_off + n0 + n) * K + k0 + 8 * c) = o;
;     }
; __device__ __forceinline__ void xcd_barrier(const XcdBarrier& b) {
;     asm volatile("s_waitcnt vmcnt(0)" ::: "memory");
;     __syncthreads();
;     if (threadIdx.x == 0) {
;         unsigned* bar = b.bar;
;         __builtin_amdgcn_s_waitcnt(0);
;         unsigned nloc = b.st[0], nx = b.st[1];
;         if (nloc == 0u) { xcd_barrier_complete(bar, b.x, nloc, nx); b.st[0] = nloc; b.st[1] = nx; }
;         const unsigned old = xb_add(&bar[XB_XSUB(b.x)], 1u);
;         const unsigned gen = old / nloc;
;         if (old + 1u == (gen + 1u) * nloc) {
.Lp0x_last_oe_B:
	s_waitcnt vmcnt(0)
	s_lshr_b32 s9, s42, 6
	s_and_b32 s12, s42, 63
	ds_write2_b32 v6, v50, v51 offset1:1
	ds_write2_b32 v6, v52, v53 offset0:2 offset1:3
	v_add_u32_e32 v0, 0x420, v6
	ds_write2_b32 v0, v54, v55 offset1:1
	ds_write2_b32 v0, v56, v57 offset0:2 offset1:3
	v_add_u32_e32 v0, 0x840, v6
	ds_write2_b32 v0, v58, v59 offset1:1
	ds_write2_b32 v0, v60, v61 offset0:2 offset1:3
	v_add_u32_e32 v0, 0xc60, v6
	ds_write2_b32 v0, v62, v63 offset1:1
	ds_write2_b32 v0, v64, v65 offset0:2 offset1:3
	v_add_u32_e32 v0, 0x1080, v6
	ds_write2_b32 v0, v66, v67 offset1:1
	ds_write2_b32 v0, v68, v69 offset0:2 offset1:3
	v_add_u32_e32 v0, 0x14a0, v6
	ds_write2_b32 v0, v70, v71 offset1:1
	ds_write2_b32 v0, v72, v73 offset0:2 offset1:3
	v_add_u32_e32 v0, 0x18c0, v6
	ds_write2_b32 v0, v74, v75 offset1:1
	ds_write2_b32 v0, v76, v77 offset0:2 offset1:3
	v_add_u32_e32 v0, 0x1ce0, v6
	ds_write2_b32 v0, v78, v79 offset1:1
	ds_write2_b32 v0, v80, v81 offset0:2 offset1:3
	s_waitcnt lgkmcnt(0)
	ds_read_b32 v90, v7 offset:0
	ds_read_b32 v91, v7 offset:132
	ds_read_b32 v92, v7 offset:264
	ds_read_b32 v93, v7 offset:396
	ds_read_b32 v94, v7 offset:528
	ds_read_b32 v95, v7 offset:660
	ds_read_b32 v96, v7 offset:792
	ds_read_b32 v97, v7 offset:924
	ds_read_b32 v98, v7 offset:32
	ds_read_b32 v99, v7 offset:164
	ds_read_b32 v100, v7 offset:296
	ds_read_b32 v101, v7 offset:428
	ds_read_b32 v102, v7 offset:560
	ds_read_b32 v103, v7 offset:692
	ds_read_b32 v104, v7 offset:824
	ds_read_b32 v105, v7 offset:956
	ds_read_b32 v106, v7 offset:64
	ds_read_b32 v107, v7 offset:196
	ds_read_b32 v108, v7 offset:328
	ds_read_b32 v109, v7 offset:460
	ds_read_b32 v110, v7 offset:592
	ds_read_b32 v111, v7 offset:724
	ds_read_b32 v112, v7 offset:856
	ds_read_b32 v113, v7 offset:988
	ds_read_b32 v114, v7 offset:96
	ds_read_b32 v115, v7 offset:228
	ds_read_b32 v116, v7 offset:360
	ds_read_b32 v117, v7 offset:492
	ds_read_b32 v118, v7 offset:624
	ds_read_b32 v119, v7 offset:756
	ds_read_b32 v120, v7 offset:888
	ds_read_b32 v121, v7 offset:1020
	s_waitcnt lgkmcnt(0)
	s_mul_i32 s34, s12, 0x20000
	s_lshl_b32 s35, s9, 7
	s_add_i32 s34, s34, s35
	s_add_u32 s40, s30, s34
	s_addc_u32 s41, s31, 0
	v_cvt_pk_bf16_f32 v122, v90, v91
	v_cvt_pk_bf16_f32 v123, v92, v93
	v_cvt_pk_bf16_f32 v124, v94, v95
	v_cvt_pk_bf16_f32 v125, v96, v97
	global_store_dwordx4 v8, v[122:125], s[40:41]
	s_add_u32 s40, s40, 0x8000
	s_addc_u32 s41, s41, 0
	v_cvt_pk_bf16_f32 v126, v98, v99
	v_cvt_pk_bf16_f32 v127, v100, v101
	v_cvt_pk_bf16_f32 v128, v102, v103
	v_cvt_pk_bf16_f32 v129, v104, v105
	global_store_dwordx4 v8, v[126:129], s[40:41]
	s_add_u32 s40, s40, 0x8000
	s_addc_u32 s41, s41, 0
	v_cvt_pk_bf16_f32 v130, v106, v107
	v_cvt_pk_bf16_f32 v131, v108, v109
	v_cvt_pk_bf16_f32 v132, v110, v111
	v_cvt_pk_bf16_f32 v133, v112, v113
	global_store_dwordx4 v8, v[130:133], s[40:41]
	s_add_u32 s40, s40, 0x8000
	s_addc_u32 s41, s41, 0
	v_cvt_pk_bf16_f32 v134, v114, v115
	v_cvt_pk_bf16_f32 v135, v116, v117
	v_cvt_pk_bf16_f32 v136, v118, v119
	v_cvt_pk_bf16_f32 v137, v120, v121
	global_store_dwordx4 v8, v[134:137], s[40:41]
.Lp0x_done_oe:
.LBB0_1317:
	v_readlane_b32 s4, v254, 0
	s_add_i32 s52, s62, 1
	v_readlane_b32 s5, v254, 1
	s_cmp_lt_i32 s52, s5
	s_cselect_b64 s[4:5], -1, 0
	s_and_b64 s[6:7], s[10:11], s[4:5]
	s_and_b64 vcc, exec, s[6:7]
	s_cbranch_vccz .LBB0_1371
	v_readlane_b32 s8, v254, 40
	v_readlane_b32 s9, v254, 41
	v_readlane_b32 s10, v254, 42
	v_readlane_b32 s11, v254, 43
	s_mov_b64 s[8:9], s[10:11]
	s_getreg_b32 s10, hwreg(HW_REG_XCC_ID, 0, 4)
	s_waitcnt vmcnt(0)
	s_waitcnt lgkmcnt(0)
	s_barrier
	s_mov_b64 s[6:7], exec
	v_readlane_b32 s12, v254, 26
	v_readlane_b32 s13, v254, 27
	s_and_b64 s[12:13], s[6:7], s[12:13]
	s_mov_b64 exec, s[12:13]
	s_cbranch_execz .LBB0_1370
	v_readlane_b32 s11, v254, 21
	s_waitcnt vmcnt(0) expcnt(0) lgkmcnt(0)
	s_and_b32 s53, s10, 15
	v_mov_b32_e32 v0, s11
	ds_read_b32 v3, v0
	v_readlane_b32 s11, v254, 22
	s_waitcnt lgkmcnt(0)
	v_cmp_ne_u32_e32 vcc, 0, v3
	v_mov_b32_e32 v0, s11
	ds_read_b32 v2, v0
	s_cbranch_vccnz .LBB0_1334
	s_add_u32 s10, s8, 0x2a2a8200
	s_addc_u32 s11, s9, 0
	s_add_u32 s12, s8, 0x2a2a8400
	s_addc_u32 s13, s9, 0
	s_add_u32 s14, s8, 0x2a2a8500
	s_addc_u32 s15, s9, 0
	s_add_u32 s16, s8, 0x2a2a8600
	s_addc_u32 s17, s9, 0
	s_add_u32 s18, s8, 0x2a2a8700
	s_addc_u32 s19, s9, 0
	s_add_u32 s20, s8, 0x2a2a8800
	s_addc_u32 s21, s9, 0
	s_add_u32 s22, s8, 0x2a2a8900
	s_addc_u32 s23, s9, 0
	s_add_u32 s24, s8, 0x2a2a8a00
	s_addc_u32 s25, s9, 0
	s_add_u32 s26, s8, 0x2a2a8b00
	s_addc_u32 s27, s9, 0
	s_add_u32 s28, s8, 0x2a2a8c00
	s_addc_u32 s29, s9, 0
	s_add_u32 s30, s8, 0x2a2a8d00
	s_addc_u32 s31, s9, 0
	s_add_u32 s34, s8, 0x2a2a8e00
	s_addc_u32 s35, s9, 0
	s_add_u32 s36, s8, 0x2a2a8f00
	s_addc_u32 s37, s9, 0
	s_add_u32 s38, s8, 0x2a2a9000
	s_addc_u32 s39, s9, 0
	s_add_u32 s40, s8, 0x2a2a9100
	s_addc_u32 s41, s9, 0
	s_add_u32 s42, s8, 0x2a2a9200
	s_addc_u32 s43, s9, 0
	s_add_u32 s44, s8, 0x2a2a9300
	s_addc_u32 s45, s9, 0
	s_mov_b32 s54, 1
	s_branch .LBB0_1322
